# P0 filter: f3 contraction for 4 columns at once with streamed weights; filter items that share output lines placed on one XCD
# speedup vs baseline: 1.2713x; 1.0217x over previous
.Lscan_done:
	s_waitcnt lgkmcnt(0)
	s_setprio 0
	s_branch .LBB0_100
.Ltramp_exit:
	s_branch .LBB0_496

.Lp0_big:
	s_cmpk_lt_u32 s25, 0xc0
	s_cbranch_scc1 .LBB0_392
	s_sub_u32 s25, s25, 0xc0
	s_and_b32 s99, s25, 7
	s_lshr_b32 s25, s25, 3
	s_mulk_i32 s99, 0x90
	s_add_i32 s25, s25, s99
	s_addk_i32 s25, 0xc1

.LBB0_479:
	s_or_b64 exec, exec, s[26:27]
	v_mul_f32_e32 v6, v5, v5
	v_fmamk_f32 v7, v6, 0xb94c1982, v198
	v_fmaak_f32 v7, v6, v7, 0xbe2aaa9d
	v_readlane_b32 s4, v252, 17
	s_lshl_b32 s26, s42, 18
	v_mul_f32_e32 v7, v6, v7
	v_readlane_b32 s8, v252, 21
	v_fmac_f32_e32 v5, v5, v7
	v_fmamk_f32 v7, v6, 0x37d75334, v199
	v_readlane_b32 s9, v252, 22
	s_add_u32 s26, s8, s26
	v_fmaak_f32 v7, v6, v7, 0x3d2aabf7
	s_addc_u32 s27, s9, 0
	s_mul_i32 s28, s42, 0x920000
	v_readlane_b32 s4, v254, 37
	v_fmaak_f32 v7, v6, v7, 0xbf000004
	s_add_u32 s28, s4, s28
	v_readlane_b32 s4, v254, 38
	v_fma_f32 v6, v6, v7, 1.0
	v_and_b32_e32 v7, 1, v4
	v_lshlrev_b32_e32 v4, 30, v4
	s_addc_u32 s29, s4, 0
	v_cmp_eq_u32_e32 vcc, 0, v7
	v_and_b32_e32 v4, 0x80000000, v4
	v_xor_b32_e32 v3, v3, v2
	s_and_b64 s[0:1], s[0:1], exec
	v_cndmask_b32_e32 v5, v6, v5, vcc
	v_xor_b32_e32 v3, v3, v4
	s_cselect_b32 s0, 0, 0x110000
	v_xor_b32_e32 v3, v3, v5
	v_cmp_class_f32_e64 vcc, v2, s89
	s_add_u32 s0, s28, s0
	s_addc_u32 s1, s29, 0
	v_cndmask_b32_e32 v2, v218, v3, vcc
	s_add_i32 s28, s50, -1
	ds_write_b32 v1, v2 offset:4160
	v_cvt_f32_u32_e32 v1, s28
	v_cvt_f32_i32_e32 v2, s51
	s_lshl_b32 s28, s50, 2
	s_or_b32 s54, s28, 64
	s_lshl_b32 s53, s50, 1
	v_div_scale_f32 v3, s[28:29], v1, v1, -v2
	v_rcp_f32_e32 v4, v3
	s_lshl_b32 s55, s42, 9
	s_cmp_eq_u32 s51, 0
	s_cselect_b64 s[28:29], -1, 0
	v_fma_f32 v5, -v3, v4, 1.0
	v_fmac_f32_e32 v4, v5, v4
	v_div_scale_f32 v5, vcc, -v2, v1, -v2
	v_mul_f32_e32 v6, v5, v4
	v_fma_f32 v7, -v3, v6, v5
	v_fmac_f32_e32 v6, v7, v4
	s_cmp_gt_i32 s51, 0
	v_fma_f32 v3, -v3, v6, v5
	s_cselect_b64 s[38:39], -1, 0
	s_or_b32 s46, s51, 1
	v_div_fmas_f32 v3, v3, v4, v6
	v_cvt_f32_i32_e32 v4, s46
	v_div_fixup_f32 v18, v3, v1, -v2
	s_sub_i32 s42, s50, s51
	s_add_i32 s40, s51, s50
	v_div_scale_f32 v2, s[36:37], v1, v1, -v4
	v_rcp_f32_e32 v3, v2
	s_ashr_i32 s43, s42, 31
	s_cmp_gt_i32 s51, -1
	s_cselect_b64 s[44:45], -1, 0
	v_fma_f32 v5, -v2, v3, 1.0
	v_fmac_f32_e32 v3, v5, v3
	v_div_scale_f32 v5, vcc, -v4, v1, -v4
	v_mul_f32_e32 v6, v5, v3
	v_fma_f32 v7, -v2, v6, v5
	v_fmac_f32_e32 v6, v7, v3
	s_or_b32 s47, s51, 2
	v_fma_f32 v2, -v2, v6, v5
	v_cvt_f32_i32_e32 v5, s47
	v_div_fmas_f32 v2, v2, v3, v6
	v_div_fixup_f32 v19, v2, v1, -v4
	s_add_i32 s56, s46, s50
	v_div_scale_f32 v2, s[36:37], v1, v1, -v5
	v_rcp_f32_e32 v3, v2
	s_sub_i32 s57, s50, s46
	s_or_b32 s46, s51, 3
	s_add_i32 s59, s47, s50
	v_fma_f32 v4, -v2, v3, 1.0
	v_fmac_f32_e32 v3, v4, v3
	v_div_scale_f32 v4, vcc, -v5, v1, -v5
	v_mul_f32_e32 v6, v4, v3
	v_fma_f32 v7, -v2, v6, v4
	v_fmac_f32_e32 v6, v7, v3
	v_fma_f32 v2, -v2, v6, v4
	v_cvt_f32_i32_e32 v4, s46
	v_div_fmas_f32 v2, v2, v3, v6
	v_div_fixup_f32 v20, v2, v1, -v5
	s_sub_i32 s60, s50, s47
	v_div_scale_f32 v2, s[36:37], v1, v1, -v4
	v_rcp_f32_e32 v3, v2
	s_or_b32 s47, s51, 4
	s_add_i32 s62, s46, s50
	s_sub_i32 s63, s50, s46
	v_fma_f32 v5, -v2, v3, 1.0
	v_fmac_f32_e32 v3, v5, v3
	v_div_scale_f32 v5, vcc, -v4, v1, -v4
	v_mul_f32_e32 v6, v5, v3
	v_fma_f32 v7, -v2, v6, v5
	v_fmac_f32_e32 v6, v7, v3
	v_fma_f32 v2, -v2, v6, v5
	v_cvt_f32_i32_e32 v5, s47
	v_div_fmas_f32 v2, v2, v3, v6
	v_div_fixup_f32 v21, v2, v1, -v4
	s_or_b32 s46, s51, 5
	v_div_scale_f32 v2, s[36:37], v1, v1, -v5
	v_rcp_f32_e32 v3, v2
	s_add_i32 s65, s47, s50
	s_sub_i32 s66, s50, s47
	s_or_b32 s47, s51, 6
	v_fma_f32 v4, -v2, v3, 1.0
	v_fmac_f32_e32 v3, v4, v3
	v_div_scale_f32 v4, vcc, -v5, v1, -v5
	v_mul_f32_e32 v6, v4, v3
	v_fma_f32 v7, -v2, v6, v4
	v_fmac_f32_e32 v6, v7, v3
	v_fma_f32 v2, -v2, v6, v4
	v_cvt_f32_i32_e32 v4, s46
	v_div_fmas_f32 v2, v2, v3, v6
	v_div_fixup_f32 v22, v2, v1, -v5
	s_add_i32 s68, s46, s50
	v_div_scale_f32 v2, s[36:37], v1, v1, -v4
	v_rcp_f32_e32 v3, v2
	s_sub_i32 s69, s50, s46
	s_or_b32 s46, s51, 7
	s_add_i32 s51, s47, s50
	v_fma_f32 v5, -v2, v3, 1.0
	v_fmac_f32_e32 v3, v5, v3
	v_div_scale_f32 v5, vcc, -v4, v1, -v4
	v_mul_f32_e32 v6, v5, v3
	v_fma_f32 v7, -v2, v6, v5
	v_fmac_f32_e32 v6, v7, v3
	v_fma_f32 v2, -v2, v6, v5
	v_cvt_f32_i32_e32 v5, s47
	v_div_fmas_f32 v2, v2, v3, v6
	v_div_fixup_f32 v23, v2, v1, -v4
	s_sub_i32 s71, s50, s47
	v_div_scale_f32 v2, s[36:37], v1, v1, -v5
	v_rcp_f32_e32 v3, v2
	s_add_i32 s89, s46, s50
	s_sub_i32 s50, s50, s46
	s_mov_b32 s52, 0
	v_fma_f32 v4, -v2, v3, 1.0
	v_fmac_f32_e32 v3, v4, v3
	v_div_scale_f32 v4, vcc, -v5, v1, -v5
	v_mul_f32_e32 v6, v4, v3
	v_fma_f32 v7, -v2, v6, v4
	v_fmac_f32_e32 v6, v7, v3
	v_fma_f32 v2, -v2, v6, v4
	v_cvt_f32_i32_e32 v4, s46
	v_div_fmas_f32 v2, v2, v3, v6
	v_div_fixup_f32 v24, v2, v1, -v5
	s_mov_b32 s41, s93
	v_div_scale_f32 v2, s[36:37], v1, v1, -v4
	v_rcp_f32_e32 v3, v2
	s_ashr_i32 s58, s57, 31
	s_ashr_i32 s61, s60, 31
	s_ashr_i32 s64, s63, 31
	v_fma_f32 v5, -v2, v3, 1.0
	v_fmac_f32_e32 v3, v5, v3
	v_div_scale_f32 v5, vcc, -v4, v1, -v4
	v_mul_f32_e32 v6, v5, v3
	v_fma_f32 v7, -v2, v6, v5
	v_fmac_f32_e32 v6, v7, v3
	v_fma_f32 v2, -v2, v6, v5
	v_div_fmas_f32 v2, v2, v3, v6
	v_div_fixup_f32 v25, v2, v1, -v4
	v_ashrrev_i32_e32 v1, 31, v0
	s_ashr_i32 s67, s66, 31
	s_ashr_i32 s70, s69, 31
	s_ashr_i32 s88, s71, 31
	s_ashr_i32 s90, s50, 31
	v_lshl_add_u64 v[2:3], v[0:1], 2, s[26:27]
	v_mov_b32_e32 v1, v0
	v_readlane_b32 s5, v252, 18
	v_readlane_b32 s6, v252, 19
	v_readlane_b32 s7, v252, 20
	v_readlane_b32 s10, v252, 23
	v_readlane_b32 s11, v252, 24
	v_readlane_b32 s12, v252, 25
	v_readlane_b32 s13, v252, 26
	v_readlane_b32 s14, v252, 27
	v_readlane_b32 s15, v252, 28
	v_readlane_b32 s16, v252, 29
	v_readlane_b32 s17, v252, 30
	v_readlane_b32 s18, v252, 31
	v_readlane_b32 s19, v252, 32
	s_waitcnt lgkmcnt(0)
	s_barrier
	v_lshlrev_b32_e32 v12, 2, v0
	s_mov_b64 s[46:47], s[26:27]
	global_load_dword v26, v12, s[46:47]
	global_load_dword v30, v12, s[46:47] offset:1024
	global_load_dword v34, v12, s[46:47] offset:2048
	global_load_dword v38, v12, s[46:47] offset:3072
	s_add_u32 s46, s46, 0x1000
	s_addc_u32 s47, s47, 0
	global_load_dword v27, v12, s[46:47]
	global_load_dword v31, v12, s[46:47] offset:1024
	global_load_dword v35, v12, s[46:47] offset:2048
	global_load_dword v39, v12, s[46:47] offset:3072
	s_add_u32 s46, s46, 0x1000
	s_addc_u32 s47, s47, 0
	global_load_dword v28, v12, s[46:47]
	global_load_dword v32, v12, s[46:47] offset:1024
	global_load_dword v36, v12, s[46:47] offset:2048
	global_load_dword v40, v12, s[46:47] offset:3072
	s_add_u32 s46, s46, 0x1000
	s_addc_u32 s47, s47, 0
	global_load_dword v29, v12, s[46:47]
	global_load_dword v33, v12, s[46:47] offset:1024
	global_load_dword v37, v12, s[46:47] offset:2048
	global_load_dword v41, v12, s[46:47] offset:3072
	s_add_u32 s46, s46, 0x1000
	s_addc_u32 s47, s47, 0
	global_load_dword v42, v12, s[46:47]
	global_load_dword v46, v12, s[46:47] offset:1024
	global_load_dword v50, v12, s[46:47] offset:2048
	global_load_dword v54, v12, s[46:47] offset:3072
	s_add_u32 s46, s46, 0x1000
	s_addc_u32 s47, s47, 0
	global_load_dword v43, v12, s[46:47]
	global_load_dword v47, v12, s[46:47] offset:1024
	global_load_dword v51, v12, s[46:47] offset:2048
	global_load_dword v55, v12, s[46:47] offset:3072
	s_add_u32 s46, s46, 0x1000
	s_addc_u32 s47, s47, 0
	global_load_dword v44, v12, s[46:47]
	global_load_dword v48, v12, s[46:47] offset:1024
	global_load_dword v52, v12, s[46:47] offset:2048
	global_load_dword v56, v12, s[46:47] offset:3072
	s_add_u32 s46, s46, 0x1000
	s_addc_u32 s47, s47, 0
	global_load_dword v45, v12, s[46:47]
	global_load_dword v49, v12, s[46:47] offset:1024
	global_load_dword v53, v12, s[46:47] offset:2048
	global_load_dword v57, v12, s[46:47] offset:3072
	s_add_u32 s46, s46, 0x1000
	s_addc_u32 s47, s47, 0
	global_load_dword v58, v12, s[46:47]
	global_load_dword v62, v12, s[46:47] offset:1024
	global_load_dword v66, v12, s[46:47] offset:2048
	global_load_dword v70, v12, s[46:47] offset:3072
	s_add_u32 s46, s46, 0x1000
	s_addc_u32 s47, s47, 0
	global_load_dword v59, v12, s[46:47]
	global_load_dword v63, v12, s[46:47] offset:1024
	global_load_dword v67, v12, s[46:47] offset:2048
	global_load_dword v71, v12, s[46:47] offset:3072
	s_add_u32 s46, s46, 0x1000
	s_addc_u32 s47, s47, 0
	global_load_dword v60, v12, s[46:47]
	global_load_dword v64, v12, s[46:47] offset:1024
	global_load_dword v68, v12, s[46:47] offset:2048
	global_load_dword v72, v12, s[46:47] offset:3072
	s_add_u32 s46, s46, 0x1000
	s_addc_u32 s47, s47, 0
	global_load_dword v61, v12, s[46:47]
	global_load_dword v65, v12, s[46:47] offset:1024
	global_load_dword v69, v12, s[46:47] offset:2048
	global_load_dword v73, v12, s[46:47] offset:3072
	s_add_u32 s46, s46, 0x1000
	s_addc_u32 s47, s47, 0
	global_load_dword v74, v12, s[46:47]
	global_load_dword v78, v12, s[46:47] offset:1024
	global_load_dword v82, v12, s[46:47] offset:2048
	global_load_dword v86, v12, s[46:47] offset:3072
	s_add_u32 s46, s46, 0x1000
	s_addc_u32 s47, s47, 0
	global_load_dword v75, v12, s[46:47]
	global_load_dword v79, v12, s[46:47] offset:1024
	global_load_dword v83, v12, s[46:47] offset:2048
	global_load_dword v87, v12, s[46:47] offset:3072
	s_add_u32 s46, s46, 0x1000
	s_addc_u32 s47, s47, 0
	global_load_dword v76, v12, s[46:47]
	global_load_dword v80, v12, s[46:47] offset:1024
	global_load_dword v84, v12, s[46:47] offset:2048
	global_load_dword v88, v12, s[46:47] offset:3072
	s_add_u32 s46, s46, 0x1000
	s_addc_u32 s47, s47, 0
	global_load_dword v77, v12, s[46:47]
	global_load_dword v81, v12, s[46:47] offset:1024
	global_load_dword v85, v12, s[46:47] offset:2048
	global_load_dword v89, v12, s[46:47] offset:3072
	s_add_u32 s46, s46, 0x1000
	s_addc_u32 s47, s47, 0
	ds_read_b128 v[90:93], v131 offset:3136
	ds_read_b128 v[94:97], v131 offset:3392
	ds_read_b128 v[98:101], v131 offset:3648
	ds_read_b128 v[102:105], v131 offset:3904
	ds_read_b128 v[106:109], v131 offset:4160
	ds_read_b128 v[110:113], v131 offset:4416
	ds_read_b128 v[114:117], v131 offset:4672
	ds_read_b128 v[118:121], v131 offset:4928
	s_waitcnt vmcnt(48)
	s_waitcnt lgkmcnt(7)
	v_pk_mul_f32 v[132:133], v[26:27], v[90:91]
	v_pk_fma_f32 v[132:133], v[28:29], v[92:93], v[132:133]
	v_pk_mul_f32 v[148:149], v[30:31], v[90:91]
	v_pk_fma_f32 v[148:149], v[32:33], v[92:93], v[148:149]
	v_pk_mul_f32 v[164:165], v[34:35], v[90:91]
	v_pk_fma_f32 v[164:165], v[36:37], v[92:93], v[164:165]
	v_pk_mul_f32 v[180:181], v[38:39], v[90:91]
	v_pk_fma_f32 v[180:181], v[40:41], v[92:93], v[180:181]
	ds_read_b128 v[90:93], v131 offset:3152
	s_waitcnt lgkmcnt(7)
	v_pk_mul_f32 v[134:135], v[26:27], v[94:95]
	v_pk_fma_f32 v[134:135], v[28:29], v[96:97], v[134:135]
	v_pk_mul_f32 v[150:151], v[30:31], v[94:95]
	v_pk_fma_f32 v[150:151], v[32:33], v[96:97], v[150:151]
	v_pk_mul_f32 v[166:167], v[34:35], v[94:95]
	v_pk_fma_f32 v[166:167], v[36:37], v[96:97], v[166:167]
	v_pk_mul_f32 v[182:183], v[38:39], v[94:95]
	v_pk_fma_f32 v[182:183], v[40:41], v[96:97], v[182:183]
	ds_read_b128 v[94:97], v131 offset:3408
	s_waitcnt lgkmcnt(7)
	v_pk_mul_f32 v[136:137], v[26:27], v[98:99]
	v_pk_fma_f32 v[136:137], v[28:29], v[100:101], v[136:137]
	v_pk_mul_f32 v[152:153], v[30:31], v[98:99]
	v_pk_fma_f32 v[152:153], v[32:33], v[100:101], v[152:153]
	v_pk_mul_f32 v[168:169], v[34:35], v[98:99]
	v_pk_fma_f32 v[168:169], v[36:37], v[100:101], v[168:169]
	v_pk_mul_f32 v[184:185], v[38:39], v[98:99]
	v_pk_fma_f32 v[184:185], v[40:41], v[100:101], v[184:185]
	ds_read_b128 v[98:101], v131 offset:3664
	s_waitcnt lgkmcnt(7)
	v_pk_mul_f32 v[138:139], v[26:27], v[102:103]
	v_pk_fma_f32 v[138:139], v[28:29], v[104:105], v[138:139]
	v_pk_mul_f32 v[154:155], v[30:31], v[102:103]
	v_pk_fma_f32 v[154:155], v[32:33], v[104:105], v[154:155]
	v_pk_mul_f32 v[170:171], v[34:35], v[102:103]
	v_pk_fma_f32 v[170:171], v[36:37], v[104:105], v[170:171]
	v_pk_mul_f32 v[186:187], v[38:39], v[102:103]
	v_pk_fma_f32 v[186:187], v[40:41], v[104:105], v[186:187]
	ds_read_b128 v[102:105], v131 offset:3920
	s_waitcnt lgkmcnt(7)
	v_pk_mul_f32 v[140:141], v[26:27], v[106:107]
	v_pk_fma_f32 v[140:141], v[28:29], v[108:109], v[140:141]
	v_pk_mul_f32 v[156:157], v[30:31], v[106:107]
	v_pk_fma_f32 v[156:157], v[32:33], v[108:109], v[156:157]
	v_pk_mul_f32 v[172:173], v[34:35], v[106:107]
	v_pk_fma_f32 v[172:173], v[36:37], v[108:109], v[172:173]
	v_pk_mul_f32 v[188:189], v[38:39], v[106:107]
	v_pk_fma_f32 v[188:189], v[40:41], v[108:109], v[188:189]
	ds_read_b128 v[106:109], v131 offset:4176
	s_waitcnt lgkmcnt(7)
	v_pk_mul_f32 v[142:143], v[26:27], v[110:111]
	v_pk_fma_f32 v[142:143], v[28:29], v[112:113], v[142:143]
	v_pk_mul_f32 v[158:159], v[30:31], v[110:111]
	v_pk_fma_f32 v[158:159], v[32:33], v[112:113], v[158:159]
	v_pk_mul_f32 v[174:175], v[34:35], v[110:111]
	v_pk_fma_f32 v[174:175], v[36:37], v[112:113], v[174:175]
	v_pk_mul_f32 v[190:191], v[38:39], v[110:111]
	v_pk_fma_f32 v[190:191], v[40:41], v[112:113], v[190:191]
	ds_read_b128 v[110:113], v131 offset:4432
	s_waitcnt lgkmcnt(7)
	v_pk_mul_f32 v[144:145], v[26:27], v[114:115]
	v_pk_fma_f32 v[144:145], v[28:29], v[116:117], v[144:145]
	v_pk_mul_f32 v[160:161], v[30:31], v[114:115]
	v_pk_fma_f32 v[160:161], v[32:33], v[116:117], v[160:161]
	v_pk_mul_f32 v[176:177], v[34:35], v[114:115]
	v_pk_fma_f32 v[176:177], v[36:37], v[116:117], v[176:177]
	v_pk_mul_f32 v[192:193], v[38:39], v[114:115]
	v_pk_fma_f32 v[192:193], v[40:41], v[116:117], v[192:193]
	ds_read_b128 v[114:117], v131 offset:4688
	s_waitcnt lgkmcnt(7)
	v_pk_mul_f32 v[146:147], v[26:27], v[118:119]
	v_pk_fma_f32 v[146:147], v[28:29], v[120:121], v[146:147]
	v_pk_mul_f32 v[162:163], v[30:31], v[118:119]
	v_pk_fma_f32 v[162:163], v[32:33], v[120:121], v[162:163]
	v_pk_mul_f32 v[178:179], v[34:35], v[118:119]
	v_pk_fma_f32 v[178:179], v[36:37], v[120:121], v[178:179]
	v_pk_mul_f32 v[194:195], v[38:39], v[118:119]
	v_pk_fma_f32 v[194:195], v[40:41], v[120:121], v[194:195]
	ds_read_b128 v[118:121], v131 offset:4944
	global_load_dword v26, v12, s[46:47]
	global_load_dword v30, v12, s[46:47] offset:1024
	global_load_dword v34, v12, s[46:47] offset:2048
	global_load_dword v38, v12, s[46:47] offset:3072
	s_add_u32 s46, s46, 0x1000
	s_addc_u32 s47, s47, 0
	global_load_dword v27, v12, s[46:47]
	global_load_dword v31, v12, s[46:47] offset:1024
	global_load_dword v35, v12, s[46:47] offset:2048
	global_load_dword v39, v12, s[46:47] offset:3072
	s_add_u32 s46, s46, 0x1000
	s_addc_u32 s47, s47, 0
	global_load_dword v28, v12, s[46:47]
	global_load_dword v32, v12, s[46:47] offset:1024
	global_load_dword v36, v12, s[46:47] offset:2048
	global_load_dword v40, v12, s[46:47] offset:3072
	s_add_u32 s46, s46, 0x1000
	s_addc_u32 s47, s47, 0
	global_load_dword v29, v12, s[46:47]
	global_load_dword v33, v12, s[46:47] offset:1024
	global_load_dword v37, v12, s[46:47] offset:2048
	global_load_dword v41, v12, s[46:47] offset:3072
	s_add_u32 s46, s46, 0x1000
	s_addc_u32 s47, s47, 0
	s_waitcnt vmcnt(48)
	s_waitcnt lgkmcnt(7)
	v_pk_fma_f32 v[132:133], v[42:43], v[90:91], v[132:133]
	v_pk_fma_f32 v[132:133], v[44:45], v[92:93], v[132:133]
	v_pk_fma_f32 v[148:149], v[46:47], v[90:91], v[148:149]
	v_pk_fma_f32 v[148:149], v[48:49], v[92:93], v[148:149]
	v_pk_fma_f32 v[164:165], v[50:51], v[90:91], v[164:165]
	v_pk_fma_f32 v[164:165], v[52:53], v[92:93], v[164:165]
	v_pk_fma_f32 v[180:181], v[54:55], v[90:91], v[180:181]
	v_pk_fma_f32 v[180:181], v[56:57], v[92:93], v[180:181]
	ds_read_b128 v[90:93], v131 offset:3168
	s_waitcnt lgkmcnt(7)
	v_pk_fma_f32 v[134:135], v[42:43], v[94:95], v[134:135]
	v_pk_fma_f32 v[134:135], v[44:45], v[96:97], v[134:135]
	v_pk_fma_f32 v[150:151], v[46:47], v[94:95], v[150:151]
	v_pk_fma_f32 v[150:151], v[48:49], v[96:97], v[150:151]
	v_pk_fma_f32 v[166:167], v[50:51], v[94:95], v[166:167]
	v_pk_fma_f32 v[166:167], v[52:53], v[96:97], v[166:167]
	v_pk_fma_f32 v[182:183], v[54:55], v[94:95], v[182:183]
	v_pk_fma_f32 v[182:183], v[56:57], v[96:97], v[182:183]
	ds_read_b128 v[94:97], v131 offset:3424
	s_waitcnt lgkmcnt(7)
	v_pk_fma_f32 v[136:137], v[42:43], v[98:99], v[136:137]
	v_pk_fma_f32 v[136:137], v[44:45], v[100:101], v[136:137]
	v_pk_fma_f32 v[152:153], v[46:47], v[98:99], v[152:153]
	v_pk_fma_f32 v[152:153], v[48:49], v[100:101], v[152:153]
	v_pk_fma_f32 v[168:169], v[50:51], v[98:99], v[168:169]
	v_pk_fma_f32 v[168:169], v[52:53], v[100:101], v[168:169]
	v_pk_fma_f32 v[184:185], v[54:55], v[98:99], v[184:185]
	v_pk_fma_f32 v[184:185], v[56:57], v[100:101], v[184:185]
	ds_read_b128 v[98:101], v131 offset:3680
	s_waitcnt lgkmcnt(7)
	v_pk_fma_f32 v[138:139], v[42:43], v[102:103], v[138:139]
	v_pk_fma_f32 v[138:139], v[44:45], v[104:105], v[138:139]
	v_pk_fma_f32 v[154:155], v[46:47], v[102:103], v[154:155]
	v_pk_fma_f32 v[154:155], v[48:49], v[104:105], v[154:155]
	v_pk_fma_f32 v[170:171], v[50:51], v[102:103], v[170:171]
	v_pk_fma_f32 v[170:171], v[52:53], v[104:105], v[170:171]
	v_pk_fma_f32 v[186:187], v[54:55], v[102:103], v[186:187]
	v_pk_fma_f32 v[186:187], v[56:57], v[104:105], v[186:187]
	ds_read_b128 v[102:105], v131 offset:3936
	s_waitcnt lgkmcnt(7)
	v_pk_fma_f32 v[140:141], v[42:43], v[106:107], v[140:141]
	v_pk_fma_f32 v[140:141], v[44:45], v[108:109], v[140:141]
	v_pk_fma_f32 v[156:157], v[46:47], v[106:107], v[156:157]
	v_pk_fma_f32 v[156:157], v[48:49], v[108:109], v[156:157]
	v_pk_fma_f32 v[172:173], v[50:51], v[106:107], v[172:173]
	v_pk_fma_f32 v[172:173], v[52:53], v[108:109], v[172:173]
	v_pk_fma_f32 v[188:189], v[54:55], v[106:107], v[188:189]
	v_pk_fma_f32 v[188:189], v[56:57], v[108:109], v[188:189]
	ds_read_b128 v[106:109], v131 offset:4192
	s_waitcnt lgkmcnt(7)
	v_pk_fma_f32 v[142:143], v[42:43], v[110:111], v[142:143]
	v_pk_fma_f32 v[142:143], v[44:45], v[112:113], v[142:143]
	v_pk_fma_f32 v[158:159], v[46:47], v[110:111], v[158:159]
	v_pk_fma_f32 v[158:159], v[48:49], v[112:113], v[158:159]
	v_pk_fma_f32 v[174:175], v[50:51], v[110:111], v[174:175]
	v_pk_fma_f32 v[174:175], v[52:53], v[112:113], v[174:175]
	v_pk_fma_f32 v[190:191], v[54:55], v[110:111], v[190:191]
	v_pk_fma_f32 v[190:191], v[56:57], v[112:113], v[190:191]
	ds_read_b128 v[110:113], v131 offset:4448
	s_waitcnt lgkmcnt(7)
	v_pk_fma_f32 v[144:145], v[42:43], v[114:115], v[144:145]
	v_pk_fma_f32 v[144:145], v[44:45], v[116:117], v[144:145]
	v_pk_fma_f32 v[160:161], v[46:47], v[114:115], v[160:161]
	v_pk_fma_f32 v[160:161], v[48:49], v[116:117], v[160:161]
	v_pk_fma_f32 v[176:177], v[50:51], v[114:115], v[176:177]
	v_pk_fma_f32 v[176:177], v[52:53], v[116:117], v[176:177]
	v_pk_fma_f32 v[192:193], v[54:55], v[114:115], v[192:193]
	v_pk_fma_f32 v[192:193], v[56:57], v[116:117], v[192:193]
	ds_read_b128 v[114:117], v131 offset:4704
	s_waitcnt lgkmcnt(7)
	v_pk_fma_f32 v[146:147], v[42:43], v[118:119], v[146:147]
	v_pk_fma_f32 v[146:147], v[44:45], v[120:121], v[146:147]
	v_pk_fma_f32 v[162:163], v[46:47], v[118:119], v[162:163]
	v_pk_fma_f32 v[162:163], v[48:49], v[120:121], v[162:163]
	v_pk_fma_f32 v[178:179], v[50:51], v[118:119], v[178:179]
	v_pk_fma_f32 v[178:179], v[52:53], v[120:121], v[178:179]
	v_pk_fma_f32 v[194:195], v[54:55], v[118:119], v[194:195]
	v_pk_fma_f32 v[194:195], v[56:57], v[120:121], v[194:195]
	ds_read_b128 v[118:121], v131 offset:4960
	global_load_dword v42, v12, s[46:47]
	global_load_dword v46, v12, s[46:47] offset:1024
	global_load_dword v50, v12, s[46:47] offset:2048
	global_load_dword v54, v12, s[46:47] offset:3072
	s_add_u32 s46, s46, 0x1000
	s_addc_u32 s47, s47, 0
	global_load_dword v43, v12, s[46:47]
	global_load_dword v47, v12, s[46:47] offset:1024
	global_load_dword v51, v12, s[46:47] offset:2048
	global_load_dword v55, v12, s[46:47] offset:3072
	s_add_u32 s46, s46, 0x1000
	s_addc_u32 s47, s47, 0
	global_load_dword v44, v12, s[46:47]
	global_load_dword v48, v12, s[46:47] offset:1024
	global_load_dword v52, v12, s[46:47] offset:2048
	global_load_dword v56, v12, s[46:47] offset:3072
	s_add_u32 s46, s46, 0x1000
	s_addc_u32 s47, s47, 0
	global_load_dword v45, v12, s[46:47]
	global_load_dword v49, v12, s[46:47] offset:1024
	global_load_dword v53, v12, s[46:47] offset:2048
	global_load_dword v57, v12, s[46:47] offset:3072
	s_add_u32 s46, s46, 0x1000
	s_addc_u32 s47, s47, 0
	s_waitcnt vmcnt(48)
	s_waitcnt lgkmcnt(7)
	v_pk_fma_f32 v[132:133], v[58:59], v[90:91], v[132:133]
	v_pk_fma_f32 v[132:133], v[60:61], v[92:93], v[132:133]
	v_pk_fma_f32 v[148:149], v[62:63], v[90:91], v[148:149]
	v_pk_fma_f32 v[148:149], v[64:65], v[92:93], v[148:149]
	v_pk_fma_f32 v[164:165], v[66:67], v[90:91], v[164:165]
	v_pk_fma_f32 v[164:165], v[68:69], v[92:93], v[164:165]
	v_pk_fma_f32 v[180:181], v[70:71], v[90:91], v[180:181]
	v_pk_fma_f32 v[180:181], v[72:73], v[92:93], v[180:181]
	ds_read_b128 v[90:93], v131 offset:3184
	s_waitcnt lgkmcnt(7)
	v_pk_fma_f32 v[134:135], v[58:59], v[94:95], v[134:135]
	v_pk_fma_f32 v[134:135], v[60:61], v[96:97], v[134:135]
	v_pk_fma_f32 v[150:151], v[62:63], v[94:95], v[150:151]
	v_pk_fma_f32 v[150:151], v[64:65], v[96:97], v[150:151]
	v_pk_fma_f32 v[166:167], v[66:67], v[94:95], v[166:167]
	v_pk_fma_f32 v[166:167], v[68:69], v[96:97], v[166:167]
	v_pk_fma_f32 v[182:183], v[70:71], v[94:95], v[182:183]
	v_pk_fma_f32 v[182:183], v[72:73], v[96:97], v[182:183]
	ds_read_b128 v[94:97], v131 offset:3440
	s_waitcnt lgkmcnt(7)
	v_pk_fma_f32 v[136:137], v[58:59], v[98:99], v[136:137]
	v_pk_fma_f32 v[136:137], v[60:61], v[100:101], v[136:137]
	v_pk_fma_f32 v[152:153], v[62:63], v[98:99], v[152:153]
	v_pk_fma_f32 v[152:153], v[64:65], v[100:101], v[152:153]
	v_pk_fma_f32 v[168:169], v[66:67], v[98:99], v[168:169]
	v_pk_fma_f32 v[168:169], v[68:69], v[100:101], v[168:169]
	v_pk_fma_f32 v[184:185], v[70:71], v[98:99], v[184:185]
	v_pk_fma_f32 v[184:185], v[72:73], v[100:101], v[184:185]
	ds_read_b128 v[98:101], v131 offset:3696
	s_waitcnt lgkmcnt(7)
	v_pk_fma_f32 v[138:139], v[58:59], v[102:103], v[138:139]
	v_pk_fma_f32 v[138:139], v[60:61], v[104:105], v[138:139]
	v_pk_fma_f32 v[154:155], v[62:63], v[102:103], v[154:155]
	v_pk_fma_f32 v[154:155], v[64:65], v[104:105], v[154:155]
	v_pk_fma_f32 v[170:171], v[66:67], v[102:103], v[170:171]
	v_pk_fma_f32 v[170:171], v[68:69], v[104:105], v[170:171]
	v_pk_fma_f32 v[186:187], v[70:71], v[102:103], v[186:187]
	v_pk_fma_f32 v[186:187], v[72:73], v[104:105], v[186:187]
	ds_read_b128 v[102:105], v131 offset:3952
	s_waitcnt lgkmcnt(7)
	v_pk_fma_f32 v[140:141], v[58:59], v[106:107], v[140:141]
	v_pk_fma_f32 v[140:141], v[60:61], v[108:109], v[140:141]
	v_pk_fma_f32 v[156:157], v[62:63], v[106:107], v[156:157]
	v_pk_fma_f32 v[156:157], v[64:65], v[108:109], v[156:157]
	v_pk_fma_f32 v[172:173], v[66:67], v[106:107], v[172:173]
	v_pk_fma_f32 v[172:173], v[68:69], v[108:109], v[172:173]
	v_pk_fma_f32 v[188:189], v[70:71], v[106:107], v[188:189]
	v_pk_fma_f32 v[188:189], v[72:73], v[108:109], v[188:189]
	ds_read_b128 v[106:109], v131 offset:4208
	s_waitcnt lgkmcnt(7)
	v_pk_fma_f32 v[142:143], v[58:59], v[110:111], v[142:143]
	v_pk_fma_f32 v[142:143], v[60:61], v[112:113], v[142:143]
	v_pk_fma_f32 v[158:159], v[62:63], v[110:111], v[158:159]
	v_pk_fma_f32 v[158:159], v[64:65], v[112:113], v[158:159]
	v_pk_fma_f32 v[174:175], v[66:67], v[110:111], v[174:175]
	v_pk_fma_f32 v[174:175], v[68:69], v[112:113], v[174:175]
	v_pk_fma_f32 v[190:191], v[70:71], v[110:111], v[190:191]
	v_pk_fma_f32 v[190:191], v[72:73], v[112:113], v[190:191]
	ds_read_b128 v[110:113], v131 offset:4464
	s_waitcnt lgkmcnt(7)
	v_pk_fma_f32 v[144:145], v[58:59], v[114:115], v[144:145]
	v_pk_fma_f32 v[144:145], v[60:61], v[116:117], v[144:145]
	v_pk_fma_f32 v[160:161], v[62:63], v[114:115], v[160:161]
	v_pk_fma_f32 v[160:161], v[64:65], v[116:117], v[160:161]
	v_pk_fma_f32 v[176:177], v[66:67], v[114:115], v[176:177]
	v_pk_fma_f32 v[176:177], v[68:69], v[116:117], v[176:177]
	v_pk_fma_f32 v[192:193], v[70:71], v[114:115], v[192:193]
	v_pk_fma_f32 v[192:193], v[72:73], v[116:117], v[192:193]
	ds_read_b128 v[114:117], v131 offset:4720
	s_waitcnt lgkmcnt(7)
	v_pk_fma_f32 v[146:147], v[58:59], v[118:119], v[146:147]
	v_pk_fma_f32 v[146:147], v[60:61], v[120:121], v[146:147]
	v_pk_fma_f32 v[162:163], v[62:63], v[118:119], v[162:163]
	v_pk_fma_f32 v[162:163], v[64:65], v[120:121], v[162:163]
	v_pk_fma_f32 v[178:179], v[66:67], v[118:119], v[178:179]
	v_pk_fma_f32 v[178:179], v[68:69], v[120:121], v[178:179]
	v_pk_fma_f32 v[194:195], v[70:71], v[118:119], v[194:195]
	v_pk_fma_f32 v[194:195], v[72:73], v[120:121], v[194:195]
	ds_read_b128 v[118:121], v131 offset:4976
	global_load_dword v58, v12, s[46:47]
	global_load_dword v62, v12, s[46:47] offset:1024
	global_load_dword v66, v12, s[46:47] offset:2048
	global_load_dword v70, v12, s[46:47] offset:3072
	s_add_u32 s46, s46, 0x1000
	s_addc_u32 s47, s47, 0
	global_load_dword v59, v12, s[46:47]
	global_load_dword v63, v12, s[46:47] offset:1024
	global_load_dword v67, v12, s[46:47] offset:2048
	global_load_dword v71, v12, s[46:47] offset:3072
	s_add_u32 s46, s46, 0x1000
	s_addc_u32 s47, s47, 0
	global_load_dword v60, v12, s[46:47]
	global_load_dword v64, v12, s[46:47] offset:1024
	global_load_dword v68, v12, s[46:47] offset:2048
	global_load_dword v72, v12, s[46:47] offset:3072
	s_add_u32 s46, s46, 0x1000
	s_addc_u32 s47, s47, 0
	global_load_dword v61, v12, s[46:47]
	global_load_dword v65, v12, s[46:47] offset:1024
	global_load_dword v69, v12, s[46:47] offset:2048
	global_load_dword v73, v12, s[46:47] offset:3072
	s_add_u32 s46, s46, 0x1000
	s_addc_u32 s47, s47, 0
	s_waitcnt vmcnt(48)
	s_waitcnt lgkmcnt(7)
	v_pk_fma_f32 v[132:133], v[74:75], v[90:91], v[132:133]
	v_pk_fma_f32 v[132:133], v[76:77], v[92:93], v[132:133]
	v_pk_fma_f32 v[148:149], v[78:79], v[90:91], v[148:149]
	v_pk_fma_f32 v[148:149], v[80:81], v[92:93], v[148:149]
	v_pk_fma_f32 v[164:165], v[82:83], v[90:91], v[164:165]
	v_pk_fma_f32 v[164:165], v[84:85], v[92:93], v[164:165]
	v_pk_fma_f32 v[180:181], v[86:87], v[90:91], v[180:181]
	v_pk_fma_f32 v[180:181], v[88:89], v[92:93], v[180:181]
	ds_read_b128 v[90:93], v131 offset:3200
	s_waitcnt lgkmcnt(7)
	v_pk_fma_f32 v[134:135], v[74:75], v[94:95], v[134:135]
	v_pk_fma_f32 v[134:135], v[76:77], v[96:97], v[134:135]
	v_pk_fma_f32 v[150:151], v[78:79], v[94:95], v[150:151]
	v_pk_fma_f32 v[150:151], v[80:81], v[96:97], v[150:151]
	v_pk_fma_f32 v[166:167], v[82:83], v[94:95], v[166:167]
	v_pk_fma_f32 v[166:167], v[84:85], v[96:97], v[166:167]
	v_pk_fma_f32 v[182:183], v[86:87], v[94:95], v[182:183]
	v_pk_fma_f32 v[182:183], v[88:89], v[96:97], v[182:183]
	ds_read_b128 v[94:97], v131 offset:3456
	s_waitcnt lgkmcnt(7)
	v_pk_fma_f32 v[136:137], v[74:75], v[98:99], v[136:137]
	v_pk_fma_f32 v[136:137], v[76:77], v[100:101], v[136:137]
	v_pk_fma_f32 v[152:153], v[78:79], v[98:99], v[152:153]
	v_pk_fma_f32 v[152:153], v[80:81], v[100:101], v[152:153]
	v_pk_fma_f32 v[168:169], v[82:83], v[98:99], v[168:169]
	v_pk_fma_f32 v[168:169], v[84:85], v[100:101], v[168:169]
	v_pk_fma_f32 v[184:185], v[86:87], v[98:99], v[184:185]
	v_pk_fma_f32 v[184:185], v[88:89], v[100:101], v[184:185]
	ds_read_b128 v[98:101], v131 offset:3712
	s_waitcnt lgkmcnt(7)
	v_pk_fma_f32 v[138:139], v[74:75], v[102:103], v[138:139]
	v_pk_fma_f32 v[138:139], v[76:77], v[104:105], v[138:139]
	v_pk_fma_f32 v[154:155], v[78:79], v[102:103], v[154:155]
	v_pk_fma_f32 v[154:155], v[80:81], v[104:105], v[154:155]
	v_pk_fma_f32 v[170:171], v[82:83], v[102:103], v[170:171]
	v_pk_fma_f32 v[170:171], v[84:85], v[104:105], v[170:171]
	v_pk_fma_f32 v[186:187], v[86:87], v[102:103], v[186:187]
	v_pk_fma_f32 v[186:187], v[88:89], v[104:105], v[186:187]
	ds_read_b128 v[102:105], v131 offset:3968
	s_waitcnt lgkmcnt(7)
	v_pk_fma_f32 v[140:141], v[74:75], v[106:107], v[140:141]
	v_pk_fma_f32 v[140:141], v[76:77], v[108:109], v[140:141]
	v_pk_fma_f32 v[156:157], v[78:79], v[106:107], v[156:157]
	v_pk_fma_f32 v[156:157], v[80:81], v[108:109], v[156:157]
	v_pk_fma_f32 v[172:173], v[82:83], v[106:107], v[172:173]
	v_pk_fma_f32 v[172:173], v[84:85], v[108:109], v[172:173]
	v_pk_fma_f32 v[188:189], v[86:87], v[106:107], v[188:189]
	v_pk_fma_f32 v[188:189], v[88:89], v[108:109], v[188:189]
	ds_read_b128 v[106:109], v131 offset:4224
	s_waitcnt lgkmcnt(7)
	v_pk_fma_f32 v[142:143], v[74:75], v[110:111], v[142:143]
	v_pk_fma_f32 v[142:143], v[76:77], v[112:113], v[142:143]
	v_pk_fma_f32 v[158:159], v[78:79], v[110:111], v[158:159]
	v_pk_fma_f32 v[158:159], v[80:81], v[112:113], v[158:159]
	v_pk_fma_f32 v[174:175], v[82:83], v[110:111], v[174:175]
	v_pk_fma_f32 v[174:175], v[84:85], v[112:113], v[174:175]
	v_pk_fma_f32 v[190:191], v[86:87], v[110:111], v[190:191]
	v_pk_fma_f32 v[190:191], v[88:89], v[112:113], v[190:191]
	ds_read_b128 v[110:113], v131 offset:4480
	s_waitcnt lgkmcnt(7)
	v_pk_fma_f32 v[144:145], v[74:75], v[114:115], v[144:145]
	v_pk_fma_f32 v[144:145], v[76:77], v[116:117], v[144:145]
	v_pk_fma_f32 v[160:161], v[78:79], v[114:115], v[160:161]
	v_pk_fma_f32 v[160:161], v[80:81], v[116:117], v[160:161]
	v_pk_fma_f32 v[176:177], v[82:83], v[114:115], v[176:177]
	v_pk_fma_f32 v[176:177], v[84:85], v[116:117], v[176:177]
	v_pk_fma_f32 v[192:193], v[86:87], v[114:115], v[192:193]
	v_pk_fma_f32 v[192:193], v[88:89], v[116:117], v[192:193]
	ds_read_b128 v[114:117], v131 offset:4736
	s_waitcnt lgkmcnt(7)
	v_pk_fma_f32 v[146:147], v[74:75], v[118:119], v[146:147]
	v_pk_fma_f32 v[146:147], v[76:77], v[120:121], v[146:147]
	v_pk_fma_f32 v[162:163], v[78:79], v[118:119], v[162:163]
	v_pk_fma_f32 v[162:163], v[80:81], v[120:121], v[162:163]
	v_pk_fma_f32 v[178:179], v[82:83], v[118:119], v[178:179]
	v_pk_fma_f32 v[178:179], v[84:85], v[120:121], v[178:179]
	v_pk_fma_f32 v[194:195], v[86:87], v[118:119], v[194:195]
	v_pk_fma_f32 v[194:195], v[88:89], v[120:121], v[194:195]
	ds_read_b128 v[118:121], v131 offset:4992
	global_load_dword v74, v12, s[46:47]
	global_load_dword v78, v12, s[46:47] offset:1024
	global_load_dword v82, v12, s[46:47] offset:2048
	global_load_dword v86, v12, s[46:47] offset:3072
	s_add_u32 s46, s46, 0x1000
	s_addc_u32 s47, s47, 0
	global_load_dword v75, v12, s[46:47]
	global_load_dword v79, v12, s[46:47] offset:1024
	global_load_dword v83, v12, s[46:47] offset:2048
	global_load_dword v87, v12, s[46:47] offset:3072
	s_add_u32 s46, s46, 0x1000
	s_addc_u32 s47, s47, 0
	global_load_dword v76, v12, s[46:47]
	global_load_dword v80, v12, s[46:47] offset:1024
	global_load_dword v84, v12, s[46:47] offset:2048
	global_load_dword v88, v12, s[46:47] offset:3072
	s_add_u32 s46, s46, 0x1000
	s_addc_u32 s47, s47, 0
	global_load_dword v77, v12, s[46:47]
	global_load_dword v81, v12, s[46:47] offset:1024
	global_load_dword v85, v12, s[46:47] offset:2048
	global_load_dword v89, v12, s[46:47] offset:3072
	s_add_u32 s46, s46, 0x1000
	s_addc_u32 s47, s47, 0
	s_waitcnt vmcnt(48)
	s_waitcnt lgkmcnt(7)
	v_pk_fma_f32 v[132:133], v[26:27], v[90:91], v[132:133]
	v_pk_fma_f32 v[132:133], v[28:29], v[92:93], v[132:133]
	v_pk_fma_f32 v[148:149], v[30:31], v[90:91], v[148:149]
	v_pk_fma_f32 v[148:149], v[32:33], v[92:93], v[148:149]
	v_pk_fma_f32 v[164:165], v[34:35], v[90:91], v[164:165]
	v_pk_fma_f32 v[164:165], v[36:37], v[92:93], v[164:165]
	v_pk_fma_f32 v[180:181], v[38:39], v[90:91], v[180:181]
	v_pk_fma_f32 v[180:181], v[40:41], v[92:93], v[180:181]
	ds_read_b128 v[90:93], v131 offset:3216
	s_waitcnt lgkmcnt(7)
	v_pk_fma_f32 v[134:135], v[26:27], v[94:95], v[134:135]
	v_pk_fma_f32 v[134:135], v[28:29], v[96:97], v[134:135]
	v_pk_fma_f32 v[150:151], v[30:31], v[94:95], v[150:151]
	v_pk_fma_f32 v[150:151], v[32:33], v[96:97], v[150:151]
	v_pk_fma_f32 v[166:167], v[34:35], v[94:95], v[166:167]
	v_pk_fma_f32 v[166:167], v[36:37], v[96:97], v[166:167]
	v_pk_fma_f32 v[182:183], v[38:39], v[94:95], v[182:183]
	v_pk_fma_f32 v[182:183], v[40:41], v[96:97], v[182:183]
	ds_read_b128 v[94:97], v131 offset:3472
	s_waitcnt lgkmcnt(7)
	v_pk_fma_f32 v[136:137], v[26:27], v[98:99], v[136:137]
	v_pk_fma_f32 v[136:137], v[28:29], v[100:101], v[136:137]
	v_pk_fma_f32 v[152:153], v[30:31], v[98:99], v[152:153]
	v_pk_fma_f32 v[152:153], v[32:33], v[100:101], v[152:153]
	v_pk_fma_f32 v[168:169], v[34:35], v[98:99], v[168:169]
	v_pk_fma_f32 v[168:169], v[36:37], v[100:101], v[168:169]
	v_pk_fma_f32 v[184:185], v[38:39], v[98:99], v[184:185]
	v_pk_fma_f32 v[184:185], v[40:41], v[100:101], v[184:185]
	ds_read_b128 v[98:101], v131 offset:3728
	s_waitcnt lgkmcnt(7)
	v_pk_fma_f32 v[138:139], v[26:27], v[102:103], v[138:139]
	v_pk_fma_f32 v[138:139], v[28:29], v[104:105], v[138:139]
	v_pk_fma_f32 v[154:155], v[30:31], v[102:103], v[154:155]
	v_pk_fma_f32 v[154:155], v[32:33], v[104:105], v[154:155]
	v_pk_fma_f32 v[170:171], v[34:35], v[102:103], v[170:171]
	v_pk_fma_f32 v[170:171], v[36:37], v[104:105], v[170:171]
	v_pk_fma_f32 v[186:187], v[38:39], v[102:103], v[186:187]
	v_pk_fma_f32 v[186:187], v[40:41], v[104:105], v[186:187]
	ds_read_b128 v[102:105], v131 offset:3984
	s_waitcnt lgkmcnt(7)
	v_pk_fma_f32 v[140:141], v[26:27], v[106:107], v[140:141]
	v_pk_fma_f32 v[140:141], v[28:29], v[108:109], v[140:141]
	v_pk_fma_f32 v[156:157], v[30:31], v[106:107], v[156:157]
	v_pk_fma_f32 v[156:157], v[32:33], v[108:109], v[156:157]
	v_pk_fma_f32 v[172:173], v[34:35], v[106:107], v[172:173]
	v_pk_fma_f32 v[172:173], v[36:37], v[108:109], v[172:173]
	v_pk_fma_f32 v[188:189], v[38:39], v[106:107], v[188:189]
	v_pk_fma_f32 v[188:189], v[40:41], v[108:109], v[188:189]
	ds_read_b128 v[106:109], v131 offset:4240
	s_waitcnt lgkmcnt(7)
	v_pk_fma_f32 v[142:143], v[26:27], v[110:111], v[142:143]
	v_pk_fma_f32 v[142:143], v[28:29], v[112:113], v[142:143]
	v_pk_fma_f32 v[158:159], v[30:31], v[110:111], v[158:159]
	v_pk_fma_f32 v[158:159], v[32:33], v[112:113], v[158:159]
	v_pk_fma_f32 v[174:175], v[34:35], v[110:111], v[174:175]
	v_pk_fma_f32 v[174:175], v[36:37], v[112:113], v[174:175]
	v_pk_fma_f32 v[190:191], v[38:39], v[110:111], v[190:191]
	v_pk_fma_f32 v[190:191], v[40:41], v[112:113], v[190:191]
	ds_read_b128 v[110:113], v131 offset:4496
	s_waitcnt lgkmcnt(7)
	v_pk_fma_f32 v[144:145], v[26:27], v[114:115], v[144:145]
	v_pk_fma_f32 v[144:145], v[28:29], v[116:117], v[144:145]
	v_pk_fma_f32 v[160:161], v[30:31], v[114:115], v[160:161]
	v_pk_fma_f32 v[160:161], v[32:33], v[116:117], v[160:161]
	v_pk_fma_f32 v[176:177], v[34:35], v[114:115], v[176:177]
	v_pk_fma_f32 v[176:177], v[36:37], v[116:117], v[176:177]
	v_pk_fma_f32 v[192:193], v[38:39], v[114:115], v[192:193]
	v_pk_fma_f32 v[192:193], v[40:41], v[116:117], v[192:193]
	ds_read_b128 v[114:117], v131 offset:4752
	s_waitcnt lgkmcnt(7)
	v_pk_fma_f32 v[146:147], v[26:27], v[118:119], v[146:147]
	v_pk_fma_f32 v[146:147], v[28:29], v[120:121], v[146:147]
	v_pk_fma_f32 v[162:163], v[30:31], v[118:119], v[162:163]
	v_pk_fma_f32 v[162:163], v[32:33], v[120:121], v[162:163]
	v_pk_fma_f32 v[178:179], v[34:35], v[118:119], v[178:179]
	v_pk_fma_f32 v[178:179], v[36:37], v[120:121], v[178:179]
	v_pk_fma_f32 v[194:195], v[38:39], v[118:119], v[194:195]
	v_pk_fma_f32 v[194:195], v[40:41], v[120:121], v[194:195]
	ds_read_b128 v[118:121], v131 offset:5008
	global_load_dword v26, v12, s[46:47]
	global_load_dword v30, v12, s[46:47] offset:1024
	global_load_dword v34, v12, s[46:47] offset:2048
	global_load_dword v38, v12, s[46:47] offset:3072
	s_add_u32 s46, s46, 0x1000
	s_addc_u32 s47, s47, 0
	global_load_dword v27, v12, s[46:47]
	global_load_dword v31, v12, s[46:47] offset:1024
	global_load_dword v35, v12, s[46:47] offset:2048
	global_load_dword v39, v12, s[46:47] offset:3072
	s_add_u32 s46, s46, 0x1000
	s_addc_u32 s47, s47, 0
	global_load_dword v28, v12, s[46:47]
	global_load_dword v32, v12, s[46:47] offset:1024
	global_load_dword v36, v12, s[46:47] offset:2048
	global_load_dword v40, v12, s[46:47] offset:3072
	s_add_u32 s46, s46, 0x1000
	s_addc_u32 s47, s47, 0
	global_load_dword v29, v12, s[46:47]
	global_load_dword v33, v12, s[46:47] offset:1024
	global_load_dword v37, v12, s[46:47] offset:2048
	global_load_dword v41, v12, s[46:47] offset:3072
	s_add_u32 s46, s46, 0x1000
	s_addc_u32 s47, s47, 0
	s_waitcnt vmcnt(48)
	s_waitcnt lgkmcnt(7)
	v_pk_fma_f32 v[132:133], v[42:43], v[90:91], v[132:133]
	v_pk_fma_f32 v[132:133], v[44:45], v[92:93], v[132:133]
	v_pk_fma_f32 v[148:149], v[46:47], v[90:91], v[148:149]
	v_pk_fma_f32 v[148:149], v[48:49], v[92:93], v[148:149]
	v_pk_fma_f32 v[164:165], v[50:51], v[90:91], v[164:165]
	v_pk_fma_f32 v[164:165], v[52:53], v[92:93], v[164:165]
	v_pk_fma_f32 v[180:181], v[54:55], v[90:91], v[180:181]
	v_pk_fma_f32 v[180:181], v[56:57], v[92:93], v[180:181]
	ds_read_b128 v[90:93], v131 offset:3232
	s_waitcnt lgkmcnt(7)
	v_pk_fma_f32 v[134:135], v[42:43], v[94:95], v[134:135]
	v_pk_fma_f32 v[134:135], v[44:45], v[96:97], v[134:135]
	v_pk_fma_f32 v[150:151], v[46:47], v[94:95], v[150:151]
	v_pk_fma_f32 v[150:151], v[48:49], v[96:97], v[150:151]
	v_pk_fma_f32 v[166:167], v[50:51], v[94:95], v[166:167]
	v_pk_fma_f32 v[166:167], v[52:53], v[96:97], v[166:167]
	v_pk_fma_f32 v[182:183], v[54:55], v[94:95], v[182:183]
	v_pk_fma_f32 v[182:183], v[56:57], v[96:97], v[182:183]
	ds_read_b128 v[94:97], v131 offset:3488
	s_waitcnt lgkmcnt(7)
	v_pk_fma_f32 v[136:137], v[42:43], v[98:99], v[136:137]
	v_pk_fma_f32 v[136:137], v[44:45], v[100:101], v[136:137]
	v_pk_fma_f32 v[152:153], v[46:47], v[98:99], v[152:153]
	v_pk_fma_f32 v[152:153], v[48:49], v[100:101], v[152:153]
	v_pk_fma_f32 v[168:169], v[50:51], v[98:99], v[168:169]
	v_pk_fma_f32 v[168:169], v[52:53], v[100:101], v[168:169]
	v_pk_fma_f32 v[184:185], v[54:55], v[98:99], v[184:185]
	v_pk_fma_f32 v[184:185], v[56:57], v[100:101], v[184:185]
	ds_read_b128 v[98:101], v131 offset:3744
	s_waitcnt lgkmcnt(7)
	v_pk_fma_f32 v[138:139], v[42:43], v[102:103], v[138:139]
	v_pk_fma_f32 v[138:139], v[44:45], v[104:105], v[138:139]
	v_pk_fma_f32 v[154:155], v[46:47], v[102:103], v[154:155]
	v_pk_fma_f32 v[154:155], v[48:49], v[104:105], v[154:155]
	v_pk_fma_f32 v[170:171], v[50:51], v[102:103], v[170:171]
	v_pk_fma_f32 v[170:171], v[52:53], v[104:105], v[170:171]
	v_pk_fma_f32 v[186:187], v[54:55], v[102:103], v[186:187]
	v_pk_fma_f32 v[186:187], v[56:57], v[104:105], v[186:187]
	ds_read_b128 v[102:105], v131 offset:4000
	s_waitcnt lgkmcnt(7)
	v_pk_fma_f32 v[140:141], v[42:43], v[106:107], v[140:141]
	v_pk_fma_f32 v[140:141], v[44:45], v[108:109], v[140:141]
	v_pk_fma_f32 v[156:157], v[46:47], v[106:107], v[156:157]
	v_pk_fma_f32 v[156:157], v[48:49], v[108:109], v[156:157]
	v_pk_fma_f32 v[172:173], v[50:51], v[106:107], v[172:173]
	v_pk_fma_f32 v[172:173], v[52:53], v[108:109], v[172:173]
	v_pk_fma_f32 v[188:189], v[54:55], v[106:107], v[188:189]
	v_pk_fma_f32 v[188:189], v[56:57], v[108:109], v[188:189]
	ds_read_b128 v[106:109], v131 offset:4256
	s_waitcnt lgkmcnt(7)
	v_pk_fma_f32 v[142:143], v[42:43], v[110:111], v[142:143]
	v_pk_fma_f32 v[142:143], v[44:45], v[112:113], v[142:143]
	v_pk_fma_f32 v[158:159], v[46:47], v[110:111], v[158:159]
	v_pk_fma_f32 v[158:159], v[48:49], v[112:113], v[158:159]
	v_pk_fma_f32 v[174:175], v[50:51], v[110:111], v[174:175]
	v_pk_fma_f32 v[174:175], v[52:53], v[112:113], v[174:175]
	v_pk_fma_f32 v[190:191], v[54:55], v[110:111], v[190:191]
	v_pk_fma_f32 v[190:191], v[56:57], v[112:113], v[190:191]
	ds_read_b128 v[110:113], v131 offset:4512
	s_waitcnt lgkmcnt(7)
	v_pk_fma_f32 v[144:145], v[42:43], v[114:115], v[144:145]
	v_pk_fma_f32 v[144:145], v[44:45], v[116:117], v[144:145]
	v_pk_fma_f32 v[160:161], v[46:47], v[114:115], v[160:161]
	v_pk_fma_f32 v[160:161], v[48:49], v[116:117], v[160:161]
	v_pk_fma_f32 v[176:177], v[50:51], v[114:115], v[176:177]
	v_pk_fma_f32 v[176:177], v[52:53], v[116:117], v[176:177]
	v_pk_fma_f32 v[192:193], v[54:55], v[114:115], v[192:193]
	v_pk_fma_f32 v[192:193], v[56:57], v[116:117], v[192:193]
	ds_read_b128 v[114:117], v131 offset:4768
	s_waitcnt lgkmcnt(7)
	v_pk_fma_f32 v[146:147], v[42:43], v[118:119], v[146:147]
	v_pk_fma_f32 v[146:147], v[44:45], v[120:121], v[146:147]
	v_pk_fma_f32 v[162:163], v[46:47], v[118:119], v[162:163]
	v_pk_fma_f32 v[162:163], v[48:49], v[120:121], v[162:163]
	v_pk_fma_f32 v[178:179], v[50:51], v[118:119], v[178:179]
	v_pk_fma_f32 v[178:179], v[52:53], v[120:121], v[178:179]
	v_pk_fma_f32 v[194:195], v[54:55], v[118:119], v[194:195]
	v_pk_fma_f32 v[194:195], v[56:57], v[120:121], v[194:195]
	ds_read_b128 v[118:121], v131 offset:5024
	global_load_dword v42, v12, s[46:47]
	global_load_dword v46, v12, s[46:47] offset:1024
	global_load_dword v50, v12, s[46:47] offset:2048
	global_load_dword v54, v12, s[46:47] offset:3072
	s_add_u32 s46, s46, 0x1000
	s_addc_u32 s47, s47, 0
	global_load_dword v43, v12, s[46:47]
	global_load_dword v47, v12, s[46:47] offset:1024
	global_load_dword v51, v12, s[46:47] offset:2048
	global_load_dword v55, v12, s[46:47] offset:3072
	s_add_u32 s46, s46, 0x1000
	s_addc_u32 s47, s47, 0
	global_load_dword v44, v12, s[46:47]
	global_load_dword v48, v12, s[46:47] offset:1024
	global_load_dword v52, v12, s[46:47] offset:2048
	global_load_dword v56, v12, s[46:47] offset:3072
	s_add_u32 s46, s46, 0x1000
	s_addc_u32 s47, s47, 0
	global_load_dword v45, v12, s[46:47]
	global_load_dword v49, v12, s[46:47] offset:1024
	global_load_dword v53, v12, s[46:47] offset:2048
	global_load_dword v57, v12, s[46:47] offset:3072
	s_add_u32 s46, s46, 0x1000
	s_addc_u32 s47, s47, 0
	s_waitcnt vmcnt(48)
	s_waitcnt lgkmcnt(7)
	v_pk_fma_f32 v[132:133], v[58:59], v[90:91], v[132:133]
	v_pk_fma_f32 v[132:133], v[60:61], v[92:93], v[132:133]
	v_pk_fma_f32 v[148:149], v[62:63], v[90:91], v[148:149]
	v_pk_fma_f32 v[148:149], v[64:65], v[92:93], v[148:149]
	v_pk_fma_f32 v[164:165], v[66:67], v[90:91], v[164:165]
	v_pk_fma_f32 v[164:165], v[68:69], v[92:93], v[164:165]
	v_pk_fma_f32 v[180:181], v[70:71], v[90:91], v[180:181]
	v_pk_fma_f32 v[180:181], v[72:73], v[92:93], v[180:181]
	ds_read_b128 v[90:93], v131 offset:3248
	s_waitcnt lgkmcnt(7)
	v_pk_fma_f32 v[134:135], v[58:59], v[94:95], v[134:135]
	v_pk_fma_f32 v[134:135], v[60:61], v[96:97], v[134:135]
	v_pk_fma_f32 v[150:151], v[62:63], v[94:95], v[150:151]
	v_pk_fma_f32 v[150:151], v[64:65], v[96:97], v[150:151]
	v_pk_fma_f32 v[166:167], v[66:67], v[94:95], v[166:167]
	v_pk_fma_f32 v[166:167], v[68:69], v[96:97], v[166:167]
	v_pk_fma_f32 v[182:183], v[70:71], v[94:95], v[182:183]
	v_pk_fma_f32 v[182:183], v[72:73], v[96:97], v[182:183]
	ds_read_b128 v[94:97], v131 offset:3504
	s_waitcnt lgkmcnt(7)
	v_pk_fma_f32 v[136:137], v[58:59], v[98:99], v[136:137]
	v_pk_fma_f32 v[136:137], v[60:61], v[100:101], v[136:137]
	v_pk_fma_f32 v[152:153], v[62:63], v[98:99], v[152:153]
	v_pk_fma_f32 v[152:153], v[64:65], v[100:101], v[152:153]
	v_pk_fma_f32 v[168:169], v[66:67], v[98:99], v[168:169]
	v_pk_fma_f32 v[168:169], v[68:69], v[100:101], v[168:169]
	v_pk_fma_f32 v[184:185], v[70:71], v[98:99], v[184:185]
	v_pk_fma_f32 v[184:185], v[72:73], v[100:101], v[184:185]
	ds_read_b128 v[98:101], v131 offset:3760
	s_waitcnt lgkmcnt(7)
	v_pk_fma_f32 v[138:139], v[58:59], v[102:103], v[138:139]
	v_pk_fma_f32 v[138:139], v[60:61], v[104:105], v[138:139]
	v_pk_fma_f32 v[154:155], v[62:63], v[102:103], v[154:155]
	v_pk_fma_f32 v[154:155], v[64:65], v[104:105], v[154:155]
	v_pk_fma_f32 v[170:171], v[66:67], v[102:103], v[170:171]
	v_pk_fma_f32 v[170:171], v[68:69], v[104:105], v[170:171]
	v_pk_fma_f32 v[186:187], v[70:71], v[102:103], v[186:187]
	v_pk_fma_f32 v[186:187], v[72:73], v[104:105], v[186:187]
	ds_read_b128 v[102:105], v131 offset:4016
	s_waitcnt lgkmcnt(7)
	v_pk_fma_f32 v[140:141], v[58:59], v[106:107], v[140:141]
	v_pk_fma_f32 v[140:141], v[60:61], v[108:109], v[140:141]
	v_pk_fma_f32 v[156:157], v[62:63], v[106:107], v[156:157]
	v_pk_fma_f32 v[156:157], v[64:65], v[108:109], v[156:157]
	v_pk_fma_f32 v[172:173], v[66:67], v[106:107], v[172:173]
	v_pk_fma_f32 v[172:173], v[68:69], v[108:109], v[172:173]
	v_pk_fma_f32 v[188:189], v[70:71], v[106:107], v[188:189]
	v_pk_fma_f32 v[188:189], v[72:73], v[108:109], v[188:189]
	ds_read_b128 v[106:109], v131 offset:4272
	s_waitcnt lgkmcnt(7)
	v_pk_fma_f32 v[142:143], v[58:59], v[110:111], v[142:143]
	v_pk_fma_f32 v[142:143], v[60:61], v[112:113], v[142:143]
	v_pk_fma_f32 v[158:159], v[62:63], v[110:111], v[158:159]
	v_pk_fma_f32 v[158:159], v[64:65], v[112:113], v[158:159]
	v_pk_fma_f32 v[174:175], v[66:67], v[110:111], v[174:175]
	v_pk_fma_f32 v[174:175], v[68:69], v[112:113], v[174:175]
	v_pk_fma_f32 v[190:191], v[70:71], v[110:111], v[190:191]
	v_pk_fma_f32 v[190:191], v[72:73], v[112:113], v[190:191]
	ds_read_b128 v[110:113], v131 offset:4528
	s_waitcnt lgkmcnt(7)
	v_pk_fma_f32 v[144:145], v[58:59], v[114:115], v[144:145]
	v_pk_fma_f32 v[144:145], v[60:61], v[116:117], v[144:145]
	v_pk_fma_f32 v[160:161], v[62:63], v[114:115], v[160:161]
	v_pk_fma_f32 v[160:161], v[64:65], v[116:117], v[160:161]
	v_pk_fma_f32 v[176:177], v[66:67], v[114:115], v[176:177]
	v_pk_fma_f32 v[176:177], v[68:69], v[116:117], v[176:177]
	v_pk_fma_f32 v[192:193], v[70:71], v[114:115], v[192:193]
	v_pk_fma_f32 v[192:193], v[72:73], v[116:117], v[192:193]
	ds_read_b128 v[114:117], v131 offset:4784
	s_waitcnt lgkmcnt(7)
	v_pk_fma_f32 v[146:147], v[58:59], v[118:119], v[146:147]
	v_pk_fma_f32 v[146:147], v[60:61], v[120:121], v[146:147]
	v_pk_fma_f32 v[162:163], v[62:63], v[118:119], v[162:163]
	v_pk_fma_f32 v[162:163], v[64:65], v[120:121], v[162:163]
	v_pk_fma_f32 v[178:179], v[66:67], v[118:119], v[178:179]
	v_pk_fma_f32 v[178:179], v[68:69], v[120:121], v[178:179]
	v_pk_fma_f32 v[194:195], v[70:71], v[118:119], v[194:195]
	v_pk_fma_f32 v[194:195], v[72:73], v[120:121], v[194:195]
	ds_read_b128 v[118:121], v131 offset:5040
	global_load_dword v58, v12, s[46:47]
	global_load_dword v62, v12, s[46:47] offset:1024
	global_load_dword v66, v12, s[46:47] offset:2048
	global_load_dword v70, v12, s[46:47] offset:3072
	s_add_u32 s46, s46, 0x1000
	s_addc_u32 s47, s47, 0
	global_load_dword v59, v12, s[46:47]
	global_load_dword v63, v12, s[46:47] offset:1024
	global_load_dword v67, v12, s[46:47] offset:2048
	global_load_dword v71, v12, s[46:47] offset:3072
	s_add_u32 s46, s46, 0x1000
	s_addc_u32 s47, s47, 0
	global_load_dword v60, v12, s[46:47]
	global_load_dword v64, v12, s[46:47] offset:1024
	global_load_dword v68, v12, s[46:47] offset:2048
	global_load_dword v72, v12, s[46:47] offset:3072
	s_add_u32 s46, s46, 0x1000
	s_addc_u32 s47, s47, 0
	global_load_dword v61, v12, s[46:47]
	global_load_dword v65, v12, s[46:47] offset:1024
	global_load_dword v69, v12, s[46:47] offset:2048
	global_load_dword v73, v12, s[46:47] offset:3072
	s_add_u32 s46, s46, 0x1000
	s_addc_u32 s47, s47, 0
	s_waitcnt vmcnt(48)
	s_waitcnt lgkmcnt(7)
	v_pk_fma_f32 v[132:133], v[74:75], v[90:91], v[132:133]
	v_pk_fma_f32 v[132:133], v[76:77], v[92:93], v[132:133]
	v_pk_fma_f32 v[148:149], v[78:79], v[90:91], v[148:149]
	v_pk_fma_f32 v[148:149], v[80:81], v[92:93], v[148:149]
	v_pk_fma_f32 v[164:165], v[82:83], v[90:91], v[164:165]
	v_pk_fma_f32 v[164:165], v[84:85], v[92:93], v[164:165]
	v_pk_fma_f32 v[180:181], v[86:87], v[90:91], v[180:181]
	v_pk_fma_f32 v[180:181], v[88:89], v[92:93], v[180:181]
	ds_read_b128 v[90:93], v131 offset:3264
	s_waitcnt lgkmcnt(7)
	v_pk_fma_f32 v[134:135], v[74:75], v[94:95], v[134:135]
	v_pk_fma_f32 v[134:135], v[76:77], v[96:97], v[134:135]
	v_pk_fma_f32 v[150:151], v[78:79], v[94:95], v[150:151]
	v_pk_fma_f32 v[150:151], v[80:81], v[96:97], v[150:151]
	v_pk_fma_f32 v[166:167], v[82:83], v[94:95], v[166:167]
	v_pk_fma_f32 v[166:167], v[84:85], v[96:97], v[166:167]
	v_pk_fma_f32 v[182:183], v[86:87], v[94:95], v[182:183]
	v_pk_fma_f32 v[182:183], v[88:89], v[96:97], v[182:183]
	ds_read_b128 v[94:97], v131 offset:3520
	s_waitcnt lgkmcnt(7)
	v_pk_fma_f32 v[136:137], v[74:75], v[98:99], v[136:137]
	v_pk_fma_f32 v[136:137], v[76:77], v[100:101], v[136:137]
	v_pk_fma_f32 v[152:153], v[78:79], v[98:99], v[152:153]
	v_pk_fma_f32 v[152:153], v[80:81], v[100:101], v[152:153]
	v_pk_fma_f32 v[168:169], v[82:83], v[98:99], v[168:169]
	v_pk_fma_f32 v[168:169], v[84:85], v[100:101], v[168:169]
	v_pk_fma_f32 v[184:185], v[86:87], v[98:99], v[184:185]
	v_pk_fma_f32 v[184:185], v[88:89], v[100:101], v[184:185]
	ds_read_b128 v[98:101], v131 offset:3776
	s_waitcnt lgkmcnt(7)
	v_pk_fma_f32 v[138:139], v[74:75], v[102:103], v[138:139]
	v_pk_fma_f32 v[138:139], v[76:77], v[104:105], v[138:139]
	v_pk_fma_f32 v[154:155], v[78:79], v[102:103], v[154:155]
	v_pk_fma_f32 v[154:155], v[80:81], v[104:105], v[154:155]
	v_pk_fma_f32 v[170:171], v[82:83], v[102:103], v[170:171]
	v_pk_fma_f32 v[170:171], v[84:85], v[104:105], v[170:171]
	v_pk_fma_f32 v[186:187], v[86:87], v[102:103], v[186:187]
	v_pk_fma_f32 v[186:187], v[88:89], v[104:105], v[186:187]
	ds_read_b128 v[102:105], v131 offset:4032
	s_waitcnt lgkmcnt(7)
	v_pk_fma_f32 v[140:141], v[74:75], v[106:107], v[140:141]
	v_pk_fma_f32 v[140:141], v[76:77], v[108:109], v[140:141]
	v_pk_fma_f32 v[156:157], v[78:79], v[106:107], v[156:157]
	v_pk_fma_f32 v[156:157], v[80:81], v[108:109], v[156:157]
	v_pk_fma_f32 v[172:173], v[82:83], v[106:107], v[172:173]
	v_pk_fma_f32 v[172:173], v[84:85], v[108:109], v[172:173]
	v_pk_fma_f32 v[188:189], v[86:87], v[106:107], v[188:189]
	v_pk_fma_f32 v[188:189], v[88:89], v[108:109], v[188:189]
	ds_read_b128 v[106:109], v131 offset:4288
	s_waitcnt lgkmcnt(7)
	v_pk_fma_f32 v[142:143], v[74:75], v[110:111], v[142:143]
	v_pk_fma_f32 v[142:143], v[76:77], v[112:113], v[142:143]
	v_pk_fma_f32 v[158:159], v[78:79], v[110:111], v[158:159]
	v_pk_fma_f32 v[158:159], v[80:81], v[112:113], v[158:159]
	v_pk_fma_f32 v[174:175], v[82:83], v[110:111], v[174:175]
	v_pk_fma_f32 v[174:175], v[84:85], v[112:113], v[174:175]
	v_pk_fma_f32 v[190:191], v[86:87], v[110:111], v[190:191]
	v_pk_fma_f32 v[190:191], v[88:89], v[112:113], v[190:191]
	ds_read_b128 v[110:113], v131 offset:4544
	s_waitcnt lgkmcnt(7)
	v_pk_fma_f32 v[144:145], v[74:75], v[114:115], v[144:145]
	v_pk_fma_f32 v[144:145], v[76:77], v[116:117], v[144:145]
	v_pk_fma_f32 v[160:161], v[78:79], v[114:115], v[160:161]
	v_pk_fma_f32 v[160:161], v[80:81], v[116:117], v[160:161]
	v_pk_fma_f32 v[176:177], v[82:83], v[114:115], v[176:177]
	v_pk_fma_f32 v[176:177], v[84:85], v[116:117], v[176:177]
	v_pk_fma_f32 v[192:193], v[86:87], v[114:115], v[192:193]
	v_pk_fma_f32 v[192:193], v[88:89], v[116:117], v[192:193]
	ds_read_b128 v[114:117], v131 offset:4800
	s_waitcnt lgkmcnt(7)
	v_pk_fma_f32 v[146:147], v[74:75], v[118:119], v[146:147]
	v_pk_fma_f32 v[146:147], v[76:77], v[120:121], v[146:147]
	v_pk_fma_f32 v[162:163], v[78:79], v[118:119], v[162:163]
	v_pk_fma_f32 v[162:163], v[80:81], v[120:121], v[162:163]
	v_pk_fma_f32 v[178:179], v[82:83], v[118:119], v[178:179]
	v_pk_fma_f32 v[178:179], v[84:85], v[120:121], v[178:179]
	v_pk_fma_f32 v[194:195], v[86:87], v[118:119], v[194:195]
	v_pk_fma_f32 v[194:195], v[88:89], v[120:121], v[194:195]
	ds_read_b128 v[118:121], v131 offset:5056
	global_load_dword v74, v12, s[46:47]
	global_load_dword v78, v12, s[46:47] offset:1024
	global_load_dword v82, v12, s[46:47] offset:2048
	global_load_dword v86, v12, s[46:47] offset:3072
	s_add_u32 s46, s46, 0x1000
	s_addc_u32 s47, s47, 0
	global_load_dword v75, v12, s[46:47]
	global_load_dword v79, v12, s[46:47] offset:1024
	global_load_dword v83, v12, s[46:47] offset:2048
	global_load_dword v87, v12, s[46:47] offset:3072
	s_add_u32 s46, s46, 0x1000
	s_addc_u32 s47, s47, 0
	global_load_dword v76, v12, s[46:47]
	global_load_dword v80, v12, s[46:47] offset:1024
	global_load_dword v84, v12, s[46:47] offset:2048
	global_load_dword v88, v12, s[46:47] offset:3072
	s_add_u32 s46, s46, 0x1000
	s_addc_u32 s47, s47, 0
	global_load_dword v77, v12, s[46:47]
	global_load_dword v81, v12, s[46:47] offset:1024
	global_load_dword v85, v12, s[46:47] offset:2048
	global_load_dword v89, v12, s[46:47] offset:3072
	s_add_u32 s46, s46, 0x1000
	s_addc_u32 s47, s47, 0
	s_waitcnt vmcnt(48)
	s_waitcnt lgkmcnt(7)
	v_pk_fma_f32 v[132:133], v[26:27], v[90:91], v[132:133]
	v_pk_fma_f32 v[132:133], v[28:29], v[92:93], v[132:133]
	v_pk_fma_f32 v[148:149], v[30:31], v[90:91], v[148:149]
	v_pk_fma_f32 v[148:149], v[32:33], v[92:93], v[148:149]
	v_pk_fma_f32 v[164:165], v[34:35], v[90:91], v[164:165]
	v_pk_fma_f32 v[164:165], v[36:37], v[92:93], v[164:165]
	v_pk_fma_f32 v[180:181], v[38:39], v[90:91], v[180:181]
	v_pk_fma_f32 v[180:181], v[40:41], v[92:93], v[180:181]
	ds_read_b128 v[90:93], v131 offset:3280
	s_waitcnt lgkmcnt(7)
	v_pk_fma_f32 v[134:135], v[26:27], v[94:95], v[134:135]
	v_pk_fma_f32 v[134:135], v[28:29], v[96:97], v[134:135]
	v_pk_fma_f32 v[150:151], v[30:31], v[94:95], v[150:151]
	v_pk_fma_f32 v[150:151], v[32:33], v[96:97], v[150:151]
	v_pk_fma_f32 v[166:167], v[34:35], v[94:95], v[166:167]
	v_pk_fma_f32 v[166:167], v[36:37], v[96:97], v[166:167]
	v_pk_fma_f32 v[182:183], v[38:39], v[94:95], v[182:183]
	v_pk_fma_f32 v[182:183], v[40:41], v[96:97], v[182:183]
	ds_read_b128 v[94:97], v131 offset:3536
	s_waitcnt lgkmcnt(7)
	v_pk_fma_f32 v[136:137], v[26:27], v[98:99], v[136:137]
	v_pk_fma_f32 v[136:137], v[28:29], v[100:101], v[136:137]
	v_pk_fma_f32 v[152:153], v[30:31], v[98:99], v[152:153]
	v_pk_fma_f32 v[152:153], v[32:33], v[100:101], v[152:153]
	v_pk_fma_f32 v[168:169], v[34:35], v[98:99], v[168:169]
	v_pk_fma_f32 v[168:169], v[36:37], v[100:101], v[168:169]
	v_pk_fma_f32 v[184:185], v[38:39], v[98:99], v[184:185]
	v_pk_fma_f32 v[184:185], v[40:41], v[100:101], v[184:185]
	ds_read_b128 v[98:101], v131 offset:3792
	s_waitcnt lgkmcnt(7)
	v_pk_fma_f32 v[138:139], v[26:27], v[102:103], v[138:139]
	v_pk_fma_f32 v[138:139], v[28:29], v[104:105], v[138:139]
	v_pk_fma_f32 v[154:155], v[30:31], v[102:103], v[154:155]
	v_pk_fma_f32 v[154:155], v[32:33], v[104:105], v[154:155]
	v_pk_fma_f32 v[170:171], v[34:35], v[102:103], v[170:171]
	v_pk_fma_f32 v[170:171], v[36:37], v[104:105], v[170:171]
	v_pk_fma_f32 v[186:187], v[38:39], v[102:103], v[186:187]
	v_pk_fma_f32 v[186:187], v[40:41], v[104:105], v[186:187]
	ds_read_b128 v[102:105], v131 offset:4048
	s_waitcnt lgkmcnt(7)
	v_pk_fma_f32 v[140:141], v[26:27], v[106:107], v[140:141]
	v_pk_fma_f32 v[140:141], v[28:29], v[108:109], v[140:141]
	v_pk_fma_f32 v[156:157], v[30:31], v[106:107], v[156:157]
	v_pk_fma_f32 v[156:157], v[32:33], v[108:109], v[156:157]
	v_pk_fma_f32 v[172:173], v[34:35], v[106:107], v[172:173]
	v_pk_fma_f32 v[172:173], v[36:37], v[108:109], v[172:173]
	v_pk_fma_f32 v[188:189], v[38:39], v[106:107], v[188:189]
	v_pk_fma_f32 v[188:189], v[40:41], v[108:109], v[188:189]
	ds_read_b128 v[106:109], v131 offset:4304
	s_waitcnt lgkmcnt(7)
	v_pk_fma_f32 v[142:143], v[26:27], v[110:111], v[142:143]
	v_pk_fma_f32 v[142:143], v[28:29], v[112:113], v[142:143]
	v_pk_fma_f32 v[158:159], v[30:31], v[110:111], v[158:159]
	v_pk_fma_f32 v[158:159], v[32:33], v[112:113], v[158:159]
	v_pk_fma_f32 v[174:175], v[34:35], v[110:111], v[174:175]
	v_pk_fma_f32 v[174:175], v[36:37], v[112:113], v[174:175]
	v_pk_fma_f32 v[190:191], v[38:39], v[110:111], v[190:191]
	v_pk_fma_f32 v[190:191], v[40:41], v[112:113], v[190:191]
	ds_read_b128 v[110:113], v131 offset:4560
	s_waitcnt lgkmcnt(7)
	v_pk_fma_f32 v[144:145], v[26:27], v[114:115], v[144:145]
	v_pk_fma_f32 v[144:145], v[28:29], v[116:117], v[144:145]
	v_pk_fma_f32 v[160:161], v[30:31], v[114:115], v[160:161]
	v_pk_fma_f32 v[160:161], v[32:33], v[116:117], v[160:161]
	v_pk_fma_f32 v[176:177], v[34:35], v[114:115], v[176:177]
	v_pk_fma_f32 v[176:177], v[36:37], v[116:117], v[176:177]
	v_pk_fma_f32 v[192:193], v[38:39], v[114:115], v[192:193]
	v_pk_fma_f32 v[192:193], v[40:41], v[116:117], v[192:193]
	ds_read_b128 v[114:117], v131 offset:4816
	s_waitcnt lgkmcnt(7)
	v_pk_fma_f32 v[146:147], v[26:27], v[118:119], v[146:147]
	v_pk_fma_f32 v[146:147], v[28:29], v[120:121], v[146:147]
	v_pk_fma_f32 v[162:163], v[30:31], v[118:119], v[162:163]
	v_pk_fma_f32 v[162:163], v[32:33], v[120:121], v[162:163]
	v_pk_fma_f32 v[178:179], v[34:35], v[118:119], v[178:179]
	v_pk_fma_f32 v[178:179], v[36:37], v[120:121], v[178:179]
	v_pk_fma_f32 v[194:195], v[38:39], v[118:119], v[194:195]
	v_pk_fma_f32 v[194:195], v[40:41], v[120:121], v[194:195]
	ds_read_b128 v[118:121], v131 offset:5072
	global_load_dword v26, v12, s[46:47]
	global_load_dword v30, v12, s[46:47] offset:1024
	global_load_dword v34, v12, s[46:47] offset:2048
	global_load_dword v38, v12, s[46:47] offset:3072
	s_add_u32 s46, s46, 0x1000
	s_addc_u32 s47, s47, 0
	global_load_dword v27, v12, s[46:47]
	global_load_dword v31, v12, s[46:47] offset:1024
	global_load_dword v35, v12, s[46:47] offset:2048
	global_load_dword v39, v12, s[46:47] offset:3072
	s_add_u32 s46, s46, 0x1000
	s_addc_u32 s47, s47, 0
	global_load_dword v28, v12, s[46:47]
	global_load_dword v32, v12, s[46:47] offset:1024
	global_load_dword v36, v12, s[46:47] offset:2048
	global_load_dword v40, v12, s[46:47] offset:3072
	s_add_u32 s46, s46, 0x1000
	s_addc_u32 s47, s47, 0
	global_load_dword v29, v12, s[46:47]
	global_load_dword v33, v12, s[46:47] offset:1024
	global_load_dword v37, v12, s[46:47] offset:2048
	global_load_dword v41, v12, s[46:47] offset:3072
	s_add_u32 s46, s46, 0x1000
	s_addc_u32 s47, s47, 0
	s_waitcnt vmcnt(48)
	s_waitcnt lgkmcnt(7)
	v_pk_fma_f32 v[132:133], v[42:43], v[90:91], v[132:133]
	v_pk_fma_f32 v[132:133], v[44:45], v[92:93], v[132:133]
	v_pk_fma_f32 v[148:149], v[46:47], v[90:91], v[148:149]
	v_pk_fma_f32 v[148:149], v[48:49], v[92:93], v[148:149]
	v_pk_fma_f32 v[164:165], v[50:51], v[90:91], v[164:165]
	v_pk_fma_f32 v[164:165], v[52:53], v[92:93], v[164:165]
	v_pk_fma_f32 v[180:181], v[54:55], v[90:91], v[180:181]
	v_pk_fma_f32 v[180:181], v[56:57], v[92:93], v[180:181]
	ds_read_b128 v[90:93], v131 offset:3296
	s_waitcnt lgkmcnt(7)
	v_pk_fma_f32 v[134:135], v[42:43], v[94:95], v[134:135]
	v_pk_fma_f32 v[134:135], v[44:45], v[96:97], v[134:135]
	v_pk_fma_f32 v[150:151], v[46:47], v[94:95], v[150:151]
	v_pk_fma_f32 v[150:151], v[48:49], v[96:97], v[150:151]
	v_pk_fma_f32 v[166:167], v[50:51], v[94:95], v[166:167]
	v_pk_fma_f32 v[166:167], v[52:53], v[96:97], v[166:167]
	v_pk_fma_f32 v[182:183], v[54:55], v[94:95], v[182:183]
	v_pk_fma_f32 v[182:183], v[56:57], v[96:97], v[182:183]
	ds_read_b128 v[94:97], v131 offset:3552
	s_waitcnt lgkmcnt(7)
	v_pk_fma_f32 v[136:137], v[42:43], v[98:99], v[136:137]
	v_pk_fma_f32 v[136:137], v[44:45], v[100:101], v[136:137]
	v_pk_fma_f32 v[152:153], v[46:47], v[98:99], v[152:153]
	v_pk_fma_f32 v[152:153], v[48:49], v[100:101], v[152:153]
	v_pk_fma_f32 v[168:169], v[50:51], v[98:99], v[168:169]
	v_pk_fma_f32 v[168:169], v[52:53], v[100:101], v[168:169]
	v_pk_fma_f32 v[184:185], v[54:55], v[98:99], v[184:185]
	v_pk_fma_f32 v[184:185], v[56:57], v[100:101], v[184:185]
	ds_read_b128 v[98:101], v131 offset:3808
	s_waitcnt lgkmcnt(7)
	v_pk_fma_f32 v[138:139], v[42:43], v[102:103], v[138:139]
	v_pk_fma_f32 v[138:139], v[44:45], v[104:105], v[138:139]
	v_pk_fma_f32 v[154:155], v[46:47], v[102:103], v[154:155]
	v_pk_fma_f32 v[154:155], v[48:49], v[104:105], v[154:155]
	v_pk_fma_f32 v[170:171], v[50:51], v[102:103], v[170:171]
	v_pk_fma_f32 v[170:171], v[52:53], v[104:105], v[170:171]
	v_pk_fma_f32 v[186:187], v[54:55], v[102:103], v[186:187]
	v_pk_fma_f32 v[186:187], v[56:57], v[104:105], v[186:187]
	ds_read_b128 v[102:105], v131 offset:4064
	s_waitcnt lgkmcnt(7)
	v_pk_fma_f32 v[140:141], v[42:43], v[106:107], v[140:141]
	v_pk_fma_f32 v[140:141], v[44:45], v[108:109], v[140:141]
	v_pk_fma_f32 v[156:157], v[46:47], v[106:107], v[156:157]
	v_pk_fma_f32 v[156:157], v[48:49], v[108:109], v[156:157]
	v_pk_fma_f32 v[172:173], v[50:51], v[106:107], v[172:173]
	v_pk_fma_f32 v[172:173], v[52:53], v[108:109], v[172:173]
	v_pk_fma_f32 v[188:189], v[54:55], v[106:107], v[188:189]
	v_pk_fma_f32 v[188:189], v[56:57], v[108:109], v[188:189]
	ds_read_b128 v[106:109], v131 offset:4320
	s_waitcnt lgkmcnt(7)
	v_pk_fma_f32 v[142:143], v[42:43], v[110:111], v[142:143]
	v_pk_fma_f32 v[142:143], v[44:45], v[112:113], v[142:143]
	v_pk_fma_f32 v[158:159], v[46:47], v[110:111], v[158:159]
	v_pk_fma_f32 v[158:159], v[48:49], v[112:113], v[158:159]
	v_pk_fma_f32 v[174:175], v[50:51], v[110:111], v[174:175]
	v_pk_fma_f32 v[174:175], v[52:53], v[112:113], v[174:175]
	v_pk_fma_f32 v[190:191], v[54:55], v[110:111], v[190:191]
	v_pk_fma_f32 v[190:191], v[56:57], v[112:113], v[190:191]
	ds_read_b128 v[110:113], v131 offset:4576
	s_waitcnt lgkmcnt(7)
	v_pk_fma_f32 v[144:145], v[42:43], v[114:115], v[144:145]
	v_pk_fma_f32 v[144:145], v[44:45], v[116:117], v[144:145]
	v_pk_fma_f32 v[160:161], v[46:47], v[114:115], v[160:161]
	v_pk_fma_f32 v[160:161], v[48:49], v[116:117], v[160:161]
	v_pk_fma_f32 v[176:177], v[50:51], v[114:115], v[176:177]
	v_pk_fma_f32 v[176:177], v[52:53], v[116:117], v[176:177]
	v_pk_fma_f32 v[192:193], v[54:55], v[114:115], v[192:193]
	v_pk_fma_f32 v[192:193], v[56:57], v[116:117], v[192:193]
	ds_read_b128 v[114:117], v131 offset:4832
	s_waitcnt lgkmcnt(7)
	v_pk_fma_f32 v[146:147], v[42:43], v[118:119], v[146:147]
	v_pk_fma_f32 v[146:147], v[44:45], v[120:121], v[146:147]
	v_pk_fma_f32 v[162:163], v[46:47], v[118:119], v[162:163]
	v_pk_fma_f32 v[162:163], v[48:49], v[120:121], v[162:163]
	v_pk_fma_f32 v[178:179], v[50:51], v[118:119], v[178:179]
	v_pk_fma_f32 v[178:179], v[52:53], v[120:121], v[178:179]
	v_pk_fma_f32 v[194:195], v[54:55], v[118:119], v[194:195]
	v_pk_fma_f32 v[194:195], v[56:57], v[120:121], v[194:195]
	ds_read_b128 v[118:121], v131 offset:5088
	global_load_dword v42, v12, s[46:47]
	global_load_dword v46, v12, s[46:47] offset:1024
	global_load_dword v50, v12, s[46:47] offset:2048
	global_load_dword v54, v12, s[46:47] offset:3072
	s_add_u32 s46, s46, 0x1000
	s_addc_u32 s47, s47, 0
	global_load_dword v43, v12, s[46:47]
	global_load_dword v47, v12, s[46:47] offset:1024
	global_load_dword v51, v12, s[46:47] offset:2048
	global_load_dword v55, v12, s[46:47] offset:3072
	s_add_u32 s46, s46, 0x1000
	s_addc_u32 s47, s47, 0
	global_load_dword v44, v12, s[46:47]
	global_load_dword v48, v12, s[46:47] offset:1024
	global_load_dword v52, v12, s[46:47] offset:2048
	global_load_dword v56, v12, s[46:47] offset:3072
	s_add_u32 s46, s46, 0x1000
	s_addc_u32 s47, s47, 0
	global_load_dword v45, v12, s[46:47]
	global_load_dword v49, v12, s[46:47] offset:1024
	global_load_dword v53, v12, s[46:47] offset:2048
	global_load_dword v57, v12, s[46:47] offset:3072
	s_add_u32 s46, s46, 0x1000
	s_addc_u32 s47, s47, 0
	s_waitcnt vmcnt(48)
	s_waitcnt lgkmcnt(7)
	v_pk_fma_f32 v[132:133], v[58:59], v[90:91], v[132:133]
	v_pk_fma_f32 v[132:133], v[60:61], v[92:93], v[132:133]
	v_pk_fma_f32 v[148:149], v[62:63], v[90:91], v[148:149]
	v_pk_fma_f32 v[148:149], v[64:65], v[92:93], v[148:149]
	v_pk_fma_f32 v[164:165], v[66:67], v[90:91], v[164:165]
	v_pk_fma_f32 v[164:165], v[68:69], v[92:93], v[164:165]
	v_pk_fma_f32 v[180:181], v[70:71], v[90:91], v[180:181]
	v_pk_fma_f32 v[180:181], v[72:73], v[92:93], v[180:181]
	ds_read_b128 v[90:93], v131 offset:3312
	s_waitcnt lgkmcnt(7)
	v_pk_fma_f32 v[134:135], v[58:59], v[94:95], v[134:135]
	v_pk_fma_f32 v[134:135], v[60:61], v[96:97], v[134:135]
	v_pk_fma_f32 v[150:151], v[62:63], v[94:95], v[150:151]
	v_pk_fma_f32 v[150:151], v[64:65], v[96:97], v[150:151]
	v_pk_fma_f32 v[166:167], v[66:67], v[94:95], v[166:167]
	v_pk_fma_f32 v[166:167], v[68:69], v[96:97], v[166:167]
	v_pk_fma_f32 v[182:183], v[70:71], v[94:95], v[182:183]
	v_pk_fma_f32 v[182:183], v[72:73], v[96:97], v[182:183]
	ds_read_b128 v[94:97], v131 offset:3568
	s_waitcnt lgkmcnt(7)
	v_pk_fma_f32 v[136:137], v[58:59], v[98:99], v[136:137]
	v_pk_fma_f32 v[136:137], v[60:61], v[100:101], v[136:137]
	v_pk_fma_f32 v[152:153], v[62:63], v[98:99], v[152:153]
	v_pk_fma_f32 v[152:153], v[64:65], v[100:101], v[152:153]
	v_pk_fma_f32 v[168:169], v[66:67], v[98:99], v[168:169]
	v_pk_fma_f32 v[168:169], v[68:69], v[100:101], v[168:169]
	v_pk_fma_f32 v[184:185], v[70:71], v[98:99], v[184:185]
	v_pk_fma_f32 v[184:185], v[72:73], v[100:101], v[184:185]
	ds_read_b128 v[98:101], v131 offset:3824
	s_waitcnt lgkmcnt(7)
	v_pk_fma_f32 v[138:139], v[58:59], v[102:103], v[138:139]
	v_pk_fma_f32 v[138:139], v[60:61], v[104:105], v[138:139]
	v_pk_fma_f32 v[154:155], v[62:63], v[102:103], v[154:155]
	v_pk_fma_f32 v[154:155], v[64:65], v[104:105], v[154:155]
	v_pk_fma_f32 v[170:171], v[66:67], v[102:103], v[170:171]
	v_pk_fma_f32 v[170:171], v[68:69], v[104:105], v[170:171]
	v_pk_fma_f32 v[186:187], v[70:71], v[102:103], v[186:187]
	v_pk_fma_f32 v[186:187], v[72:73], v[104:105], v[186:187]
	ds_read_b128 v[102:105], v131 offset:4080
	s_waitcnt lgkmcnt(7)
	v_pk_fma_f32 v[140:141], v[58:59], v[106:107], v[140:141]
	v_pk_fma_f32 v[140:141], v[60:61], v[108:109], v[140:141]
	v_pk_fma_f32 v[156:157], v[62:63], v[106:107], v[156:157]
	v_pk_fma_f32 v[156:157], v[64:65], v[108:109], v[156:157]
	v_pk_fma_f32 v[172:173], v[66:67], v[106:107], v[172:173]
	v_pk_fma_f32 v[172:173], v[68:69], v[108:109], v[172:173]
	v_pk_fma_f32 v[188:189], v[70:71], v[106:107], v[188:189]
	v_pk_fma_f32 v[188:189], v[72:73], v[108:109], v[188:189]
	ds_read_b128 v[106:109], v131 offset:4336
	s_waitcnt lgkmcnt(7)
	v_pk_fma_f32 v[142:143], v[58:59], v[110:111], v[142:143]
	v_pk_fma_f32 v[142:143], v[60:61], v[112:113], v[142:143]
	v_pk_fma_f32 v[158:159], v[62:63], v[110:111], v[158:159]
	v_pk_fma_f32 v[158:159], v[64:65], v[112:113], v[158:159]
	v_pk_fma_f32 v[174:175], v[66:67], v[110:111], v[174:175]
	v_pk_fma_f32 v[174:175], v[68:69], v[112:113], v[174:175]
	v_pk_fma_f32 v[190:191], v[70:71], v[110:111], v[190:191]
	v_pk_fma_f32 v[190:191], v[72:73], v[112:113], v[190:191]
	ds_read_b128 v[110:113], v131 offset:4592
	s_waitcnt lgkmcnt(7)
	v_pk_fma_f32 v[144:145], v[58:59], v[114:115], v[144:145]
	v_pk_fma_f32 v[144:145], v[60:61], v[116:117], v[144:145]
	v_pk_fma_f32 v[160:161], v[62:63], v[114:115], v[160:161]
	v_pk_fma_f32 v[160:161], v[64:65], v[116:117], v[160:161]
	v_pk_fma_f32 v[176:177], v[66:67], v[114:115], v[176:177]
	v_pk_fma_f32 v[176:177], v[68:69], v[116:117], v[176:177]
	v_pk_fma_f32 v[192:193], v[70:71], v[114:115], v[192:193]
	v_pk_fma_f32 v[192:193], v[72:73], v[116:117], v[192:193]
	ds_read_b128 v[114:117], v131 offset:4848
	s_waitcnt lgkmcnt(7)
	v_pk_fma_f32 v[146:147], v[58:59], v[118:119], v[146:147]
	v_pk_fma_f32 v[146:147], v[60:61], v[120:121], v[146:147]
	v_pk_fma_f32 v[162:163], v[62:63], v[118:119], v[162:163]
	v_pk_fma_f32 v[162:163], v[64:65], v[120:121], v[162:163]
	v_pk_fma_f32 v[178:179], v[66:67], v[118:119], v[178:179]
	v_pk_fma_f32 v[178:179], v[68:69], v[120:121], v[178:179]
	v_pk_fma_f32 v[194:195], v[70:71], v[118:119], v[194:195]
	v_pk_fma_f32 v[194:195], v[72:73], v[120:121], v[194:195]
	ds_read_b128 v[118:121], v131 offset:5104
	global_load_dword v58, v12, s[46:47]
	global_load_dword v62, v12, s[46:47] offset:1024
	global_load_dword v66, v12, s[46:47] offset:2048
	global_load_dword v70, v12, s[46:47] offset:3072
	s_add_u32 s46, s46, 0x1000
	s_addc_u32 s47, s47, 0
	global_load_dword v59, v12, s[46:47]
	global_load_dword v63, v12, s[46:47] offset:1024
	global_load_dword v67, v12, s[46:47] offset:2048
	global_load_dword v71, v12, s[46:47] offset:3072
	s_add_u32 s46, s46, 0x1000
	s_addc_u32 s47, s47, 0
	global_load_dword v60, v12, s[46:47]
	global_load_dword v64, v12, s[46:47] offset:1024
	global_load_dword v68, v12, s[46:47] offset:2048
	global_load_dword v72, v12, s[46:47] offset:3072
	s_add_u32 s46, s46, 0x1000
	s_addc_u32 s47, s47, 0
	global_load_dword v61, v12, s[46:47]
	global_load_dword v65, v12, s[46:47] offset:1024
	global_load_dword v69, v12, s[46:47] offset:2048
	global_load_dword v73, v12, s[46:47] offset:3072
	s_add_u32 s46, s46, 0x1000
	s_addc_u32 s47, s47, 0
	s_waitcnt vmcnt(48)
	s_waitcnt lgkmcnt(7)
	v_pk_fma_f32 v[132:133], v[74:75], v[90:91], v[132:133]
	v_pk_fma_f32 v[132:133], v[76:77], v[92:93], v[132:133]
	v_pk_fma_f32 v[148:149], v[78:79], v[90:91], v[148:149]
	v_pk_fma_f32 v[148:149], v[80:81], v[92:93], v[148:149]
	v_pk_fma_f32 v[164:165], v[82:83], v[90:91], v[164:165]
	v_pk_fma_f32 v[164:165], v[84:85], v[92:93], v[164:165]
	v_pk_fma_f32 v[180:181], v[86:87], v[90:91], v[180:181]
	v_pk_fma_f32 v[180:181], v[88:89], v[92:93], v[180:181]
	ds_read_b128 v[90:93], v131 offset:3328
	s_waitcnt lgkmcnt(7)
	v_pk_fma_f32 v[134:135], v[74:75], v[94:95], v[134:135]
	v_pk_fma_f32 v[134:135], v[76:77], v[96:97], v[134:135]
	v_pk_fma_f32 v[150:151], v[78:79], v[94:95], v[150:151]
	v_pk_fma_f32 v[150:151], v[80:81], v[96:97], v[150:151]
	v_pk_fma_f32 v[166:167], v[82:83], v[94:95], v[166:167]
	v_pk_fma_f32 v[166:167], v[84:85], v[96:97], v[166:167]
	v_pk_fma_f32 v[182:183], v[86:87], v[94:95], v[182:183]
	v_pk_fma_f32 v[182:183], v[88:89], v[96:97], v[182:183]
	ds_read_b128 v[94:97], v131 offset:3584
	s_waitcnt lgkmcnt(7)
	v_pk_fma_f32 v[136:137], v[74:75], v[98:99], v[136:137]
	v_pk_fma_f32 v[136:137], v[76:77], v[100:101], v[136:137]
	v_pk_fma_f32 v[152:153], v[78:79], v[98:99], v[152:153]
	v_pk_fma_f32 v[152:153], v[80:81], v[100:101], v[152:153]
	v_pk_fma_f32 v[168:169], v[82:83], v[98:99], v[168:169]
	v_pk_fma_f32 v[168:169], v[84:85], v[100:101], v[168:169]
	v_pk_fma_f32 v[184:185], v[86:87], v[98:99], v[184:185]
	v_pk_fma_f32 v[184:185], v[88:89], v[100:101], v[184:185]
	ds_read_b128 v[98:101], v131 offset:3840
	s_waitcnt lgkmcnt(7)
	v_pk_fma_f32 v[138:139], v[74:75], v[102:103], v[138:139]
	v_pk_fma_f32 v[138:139], v[76:77], v[104:105], v[138:139]
	v_pk_fma_f32 v[154:155], v[78:79], v[102:103], v[154:155]
	v_pk_fma_f32 v[154:155], v[80:81], v[104:105], v[154:155]
	v_pk_fma_f32 v[170:171], v[82:83], v[102:103], v[170:171]
	v_pk_fma_f32 v[170:171], v[84:85], v[104:105], v[170:171]
	v_pk_fma_f32 v[186:187], v[86:87], v[102:103], v[186:187]
	v_pk_fma_f32 v[186:187], v[88:89], v[104:105], v[186:187]
	ds_read_b128 v[102:105], v131 offset:4096
	s_waitcnt lgkmcnt(7)
	v_pk_fma_f32 v[140:141], v[74:75], v[106:107], v[140:141]
	v_pk_fma_f32 v[140:141], v[76:77], v[108:109], v[140:141]
	v_pk_fma_f32 v[156:157], v[78:79], v[106:107], v[156:157]
	v_pk_fma_f32 v[156:157], v[80:81], v[108:109], v[156:157]
	v_pk_fma_f32 v[172:173], v[82:83], v[106:107], v[172:173]
	v_pk_fma_f32 v[172:173], v[84:85], v[108:109], v[172:173]
	v_pk_fma_f32 v[188:189], v[86:87], v[106:107], v[188:189]
	v_pk_fma_f32 v[188:189], v[88:89], v[108:109], v[188:189]
	ds_read_b128 v[106:109], v131 offset:4352
	s_waitcnt lgkmcnt(7)
	v_pk_fma_f32 v[142:143], v[74:75], v[110:111], v[142:143]
	v_pk_fma_f32 v[142:143], v[76:77], v[112:113], v[142:143]
	v_pk_fma_f32 v[158:159], v[78:79], v[110:111], v[158:159]
	v_pk_fma_f32 v[158:159], v[80:81], v[112:113], v[158:159]
	v_pk_fma_f32 v[174:175], v[82:83], v[110:111], v[174:175]
	v_pk_fma_f32 v[174:175], v[84:85], v[112:113], v[174:175]
	v_pk_fma_f32 v[190:191], v[86:87], v[110:111], v[190:191]
	v_pk_fma_f32 v[190:191], v[88:89], v[112:113], v[190:191]
	ds_read_b128 v[110:113], v131 offset:4608
	s_waitcnt lgkmcnt(7)
	v_pk_fma_f32 v[144:145], v[74:75], v[114:115], v[144:145]
	v_pk_fma_f32 v[144:145], v[76:77], v[116:117], v[144:145]
	v_pk_fma_f32 v[160:161], v[78:79], v[114:115], v[160:161]
	v_pk_fma_f32 v[160:161], v[80:81], v[116:117], v[160:161]
	v_pk_fma_f32 v[176:177], v[82:83], v[114:115], v[176:177]
	v_pk_fma_f32 v[176:177], v[84:85], v[116:117], v[176:177]
	v_pk_fma_f32 v[192:193], v[86:87], v[114:115], v[192:193]
	v_pk_fma_f32 v[192:193], v[88:89], v[116:117], v[192:193]
	ds_read_b128 v[114:117], v131 offset:4864
	s_waitcnt lgkmcnt(7)
	v_pk_fma_f32 v[146:147], v[74:75], v[118:119], v[146:147]
	v_pk_fma_f32 v[146:147], v[76:77], v[120:121], v[146:147]
	v_pk_fma_f32 v[162:163], v[78:79], v[118:119], v[162:163]
	v_pk_fma_f32 v[162:163], v[80:81], v[120:121], v[162:163]
	v_pk_fma_f32 v[178:179], v[82:83], v[118:119], v[178:179]
	v_pk_fma_f32 v[178:179], v[84:85], v[120:121], v[178:179]
	v_pk_fma_f32 v[194:195], v[86:87], v[118:119], v[194:195]
	v_pk_fma_f32 v[194:195], v[88:89], v[120:121], v[194:195]
	ds_read_b128 v[118:121], v131 offset:5120
	global_load_dword v74, v12, s[46:47]
	global_load_dword v78, v12, s[46:47] offset:1024
	global_load_dword v82, v12, s[46:47] offset:2048
	global_load_dword v86, v12, s[46:47] offset:3072
	s_add_u32 s46, s46, 0x1000
	s_addc_u32 s47, s47, 0
	global_load_dword v75, v12, s[46:47]
	global_load_dword v79, v12, s[46:47] offset:1024
	global_load_dword v83, v12, s[46:47] offset:2048
	global_load_dword v87, v12, s[46:47] offset:3072
	s_add_u32 s46, s46, 0x1000
	s_addc_u32 s47, s47, 0
	global_load_dword v76, v12, s[46:47]
	global_load_dword v80, v12, s[46:47] offset:1024
	global_load_dword v84, v12, s[46:47] offset:2048
	global_load_dword v88, v12, s[46:47] offset:3072
	s_add_u32 s46, s46, 0x1000
	s_addc_u32 s47, s47, 0
	global_load_dword v77, v12, s[46:47]
	global_load_dword v81, v12, s[46:47] offset:1024
	global_load_dword v85, v12, s[46:47] offset:2048
	global_load_dword v89, v12, s[46:47] offset:3072
	s_add_u32 s46, s46, 0x1000
	s_addc_u32 s47, s47, 0
	s_waitcnt vmcnt(48)
	s_waitcnt lgkmcnt(7)
	v_pk_fma_f32 v[132:133], v[26:27], v[90:91], v[132:133]
	v_pk_fma_f32 v[132:133], v[28:29], v[92:93], v[132:133]
	v_pk_fma_f32 v[148:149], v[30:31], v[90:91], v[148:149]
	v_pk_fma_f32 v[148:149], v[32:33], v[92:93], v[148:149]
	v_pk_fma_f32 v[164:165], v[34:35], v[90:91], v[164:165]
	v_pk_fma_f32 v[164:165], v[36:37], v[92:93], v[164:165]
	v_pk_fma_f32 v[180:181], v[38:39], v[90:91], v[180:181]
	v_pk_fma_f32 v[180:181], v[40:41], v[92:93], v[180:181]
	ds_read_b128 v[90:93], v131 offset:3344
	s_waitcnt lgkmcnt(7)
	v_pk_fma_f32 v[134:135], v[26:27], v[94:95], v[134:135]
	v_pk_fma_f32 v[134:135], v[28:29], v[96:97], v[134:135]
	v_pk_fma_f32 v[150:151], v[30:31], v[94:95], v[150:151]
	v_pk_fma_f32 v[150:151], v[32:33], v[96:97], v[150:151]
	v_pk_fma_f32 v[166:167], v[34:35], v[94:95], v[166:167]
	v_pk_fma_f32 v[166:167], v[36:37], v[96:97], v[166:167]
	v_pk_fma_f32 v[182:183], v[38:39], v[94:95], v[182:183]
	v_pk_fma_f32 v[182:183], v[40:41], v[96:97], v[182:183]
	ds_read_b128 v[94:97], v131 offset:3600
	s_waitcnt lgkmcnt(7)
	v_pk_fma_f32 v[136:137], v[26:27], v[98:99], v[136:137]
	v_pk_fma_f32 v[136:137], v[28:29], v[100:101], v[136:137]
	v_pk_fma_f32 v[152:153], v[30:31], v[98:99], v[152:153]
	v_pk_fma_f32 v[152:153], v[32:33], v[100:101], v[152:153]
	v_pk_fma_f32 v[168:169], v[34:35], v[98:99], v[168:169]
	v_pk_fma_f32 v[168:169], v[36:37], v[100:101], v[168:169]
	v_pk_fma_f32 v[184:185], v[38:39], v[98:99], v[184:185]
	v_pk_fma_f32 v[184:185], v[40:41], v[100:101], v[184:185]
	ds_read_b128 v[98:101], v131 offset:3856
	s_waitcnt lgkmcnt(7)
	v_pk_fma_f32 v[138:139], v[26:27], v[102:103], v[138:139]
	v_pk_fma_f32 v[138:139], v[28:29], v[104:105], v[138:139]
	v_pk_fma_f32 v[154:155], v[30:31], v[102:103], v[154:155]
	v_pk_fma_f32 v[154:155], v[32:33], v[104:105], v[154:155]
	v_pk_fma_f32 v[170:171], v[34:35], v[102:103], v[170:171]
	v_pk_fma_f32 v[170:171], v[36:37], v[104:105], v[170:171]
	v_pk_fma_f32 v[186:187], v[38:39], v[102:103], v[186:187]
	v_pk_fma_f32 v[186:187], v[40:41], v[104:105], v[186:187]
	ds_read_b128 v[102:105], v131 offset:4112
	s_waitcnt lgkmcnt(7)
	v_pk_fma_f32 v[140:141], v[26:27], v[106:107], v[140:141]
	v_pk_fma_f32 v[140:141], v[28:29], v[108:109], v[140:141]
	v_pk_fma_f32 v[156:157], v[30:31], v[106:107], v[156:157]
	v_pk_fma_f32 v[156:157], v[32:33], v[108:109], v[156:157]
	v_pk_fma_f32 v[172:173], v[34:35], v[106:107], v[172:173]
	v_pk_fma_f32 v[172:173], v[36:37], v[108:109], v[172:173]
	v_pk_fma_f32 v[188:189], v[38:39], v[106:107], v[188:189]
	v_pk_fma_f32 v[188:189], v[40:41], v[108:109], v[188:189]
	ds_read_b128 v[106:109], v131 offset:4368
	s_waitcnt lgkmcnt(7)
	v_pk_fma_f32 v[142:143], v[26:27], v[110:111], v[142:143]
	v_pk_fma_f32 v[142:143], v[28:29], v[112:113], v[142:143]
	v_pk_fma_f32 v[158:159], v[30:31], v[110:111], v[158:159]
	v_pk_fma_f32 v[158:159], v[32:33], v[112:113], v[158:159]
	v_pk_fma_f32 v[174:175], v[34:35], v[110:111], v[174:175]
	v_pk_fma_f32 v[174:175], v[36:37], v[112:113], v[174:175]
	v_pk_fma_f32 v[190:191], v[38:39], v[110:111], v[190:191]
	v_pk_fma_f32 v[190:191], v[40:41], v[112:113], v[190:191]
	ds_read_b128 v[110:113], v131 offset:4624
	s_waitcnt lgkmcnt(7)
	v_pk_fma_f32 v[144:145], v[26:27], v[114:115], v[144:145]
	v_pk_fma_f32 v[144:145], v[28:29], v[116:117], v[144:145]
	v_pk_fma_f32 v[160:161], v[30:31], v[114:115], v[160:161]
	v_pk_fma_f32 v[160:161], v[32:33], v[116:117], v[160:161]
	v_pk_fma_f32 v[176:177], v[34:35], v[114:115], v[176:177]
	v_pk_fma_f32 v[176:177], v[36:37], v[116:117], v[176:177]
	v_pk_fma_f32 v[192:193], v[38:39], v[114:115], v[192:193]
	v_pk_fma_f32 v[192:193], v[40:41], v[116:117], v[192:193]
	ds_read_b128 v[114:117], v131 offset:4880
	s_waitcnt lgkmcnt(7)
	v_pk_fma_f32 v[146:147], v[26:27], v[118:119], v[146:147]
	v_pk_fma_f32 v[146:147], v[28:29], v[120:121], v[146:147]
	v_pk_fma_f32 v[162:163], v[30:31], v[118:119], v[162:163]
	v_pk_fma_f32 v[162:163], v[32:33], v[120:121], v[162:163]
	v_pk_fma_f32 v[178:179], v[34:35], v[118:119], v[178:179]
	v_pk_fma_f32 v[178:179], v[36:37], v[120:121], v[178:179]
	v_pk_fma_f32 v[194:195], v[38:39], v[118:119], v[194:195]
	v_pk_fma_f32 v[194:195], v[40:41], v[120:121], v[194:195]
	ds_read_b128 v[118:121], v131 offset:5136
	s_waitcnt vmcnt(32)
	s_waitcnt lgkmcnt(7)
	v_pk_fma_f32 v[132:133], v[42:43], v[90:91], v[132:133]
	v_pk_fma_f32 v[132:133], v[44:45], v[92:93], v[132:133]
	v_pk_fma_f32 v[148:149], v[46:47], v[90:91], v[148:149]
	v_pk_fma_f32 v[148:149], v[48:49], v[92:93], v[148:149]
	v_pk_fma_f32 v[164:165], v[50:51], v[90:91], v[164:165]
	v_pk_fma_f32 v[164:165], v[52:53], v[92:93], v[164:165]
	v_pk_fma_f32 v[180:181], v[54:55], v[90:91], v[180:181]
	v_pk_fma_f32 v[180:181], v[56:57], v[92:93], v[180:181]
	ds_read_b128 v[90:93], v131 offset:3360
	s_waitcnt lgkmcnt(7)
	v_pk_fma_f32 v[134:135], v[42:43], v[94:95], v[134:135]
	v_pk_fma_f32 v[134:135], v[44:45], v[96:97], v[134:135]
	v_pk_fma_f32 v[150:151], v[46:47], v[94:95], v[150:151]
	v_pk_fma_f32 v[150:151], v[48:49], v[96:97], v[150:151]
	v_pk_fma_f32 v[166:167], v[50:51], v[94:95], v[166:167]
	v_pk_fma_f32 v[166:167], v[52:53], v[96:97], v[166:167]
	v_pk_fma_f32 v[182:183], v[54:55], v[94:95], v[182:183]
	v_pk_fma_f32 v[182:183], v[56:57], v[96:97], v[182:183]
	ds_read_b128 v[94:97], v131 offset:3616
	s_waitcnt lgkmcnt(7)
	v_pk_fma_f32 v[136:137], v[42:43], v[98:99], v[136:137]
	v_pk_fma_f32 v[136:137], v[44:45], v[100:101], v[136:137]
	v_pk_fma_f32 v[152:153], v[46:47], v[98:99], v[152:153]
	v_pk_fma_f32 v[152:153], v[48:49], v[100:101], v[152:153]
	v_pk_fma_f32 v[168:169], v[50:51], v[98:99], v[168:169]
	v_pk_fma_f32 v[168:169], v[52:53], v[100:101], v[168:169]
	v_pk_fma_f32 v[184:185], v[54:55], v[98:99], v[184:185]
	v_pk_fma_f32 v[184:185], v[56:57], v[100:101], v[184:185]
	ds_read_b128 v[98:101], v131 offset:3872
	s_waitcnt lgkmcnt(7)
	v_pk_fma_f32 v[138:139], v[42:43], v[102:103], v[138:139]
	v_pk_fma_f32 v[138:139], v[44:45], v[104:105], v[138:139]
	v_pk_fma_f32 v[154:155], v[46:47], v[102:103], v[154:155]
	v_pk_fma_f32 v[154:155], v[48:49], v[104:105], v[154:155]
	v_pk_fma_f32 v[170:171], v[50:51], v[102:103], v[170:171]
	v_pk_fma_f32 v[170:171], v[52:53], v[104:105], v[170:171]
	v_pk_fma_f32 v[186:187], v[54:55], v[102:103], v[186:187]
	v_pk_fma_f32 v[186:187], v[56:57], v[104:105], v[186:187]
	ds_read_b128 v[102:105], v131 offset:4128
	s_waitcnt lgkmcnt(7)
	v_pk_fma_f32 v[140:141], v[42:43], v[106:107], v[140:141]
	v_pk_fma_f32 v[140:141], v[44:45], v[108:109], v[140:141]
	v_pk_fma_f32 v[156:157], v[46:47], v[106:107], v[156:157]
	v_pk_fma_f32 v[156:157], v[48:49], v[108:109], v[156:157]
	v_pk_fma_f32 v[172:173], v[50:51], v[106:107], v[172:173]
	v_pk_fma_f32 v[172:173], v[52:53], v[108:109], v[172:173]
	v_pk_fma_f32 v[188:189], v[54:55], v[106:107], v[188:189]
	v_pk_fma_f32 v[188:189], v[56:57], v[108:109], v[188:189]
	ds_read_b128 v[106:109], v131 offset:4384
	s_waitcnt lgkmcnt(7)
	v_pk_fma_f32 v[142:143], v[42:43], v[110:111], v[142:143]
	v_pk_fma_f32 v[142:143], v[44:45], v[112:113], v[142:143]
	v_pk_fma_f32 v[158:159], v[46:47], v[110:111], v[158:159]
	v_pk_fma_f32 v[158:159], v[48:49], v[112:113], v[158:159]
	v_pk_fma_f32 v[174:175], v[50:51], v[110:111], v[174:175]
	v_pk_fma_f32 v[174:175], v[52:53], v[112:113], v[174:175]
	v_pk_fma_f32 v[190:191], v[54:55], v[110:111], v[190:191]
	v_pk_fma_f32 v[190:191], v[56:57], v[112:113], v[190:191]
	ds_read_b128 v[110:113], v131 offset:4640
	s_waitcnt lgkmcnt(7)
	v_pk_fma_f32 v[144:145], v[42:43], v[114:115], v[144:145]
	v_pk_fma_f32 v[144:145], v[44:45], v[116:117], v[144:145]
	v_pk_fma_f32 v[160:161], v[46:47], v[114:115], v[160:161]
	v_pk_fma_f32 v[160:161], v[48:49], v[116:117], v[160:161]
	v_pk_fma_f32 v[176:177], v[50:51], v[114:115], v[176:177]
	v_pk_fma_f32 v[176:177], v[52:53], v[116:117], v[176:177]
	v_pk_fma_f32 v[192:193], v[54:55], v[114:115], v[192:193]
	v_pk_fma_f32 v[192:193], v[56:57], v[116:117], v[192:193]
	ds_read_b128 v[114:117], v131 offset:4896
	s_waitcnt lgkmcnt(7)
	v_pk_fma_f32 v[146:147], v[42:43], v[118:119], v[146:147]
	v_pk_fma_f32 v[146:147], v[44:45], v[120:121], v[146:147]
	v_pk_fma_f32 v[162:163], v[46:47], v[118:119], v[162:163]
	v_pk_fma_f32 v[162:163], v[48:49], v[120:121], v[162:163]
	v_pk_fma_f32 v[178:179], v[50:51], v[118:119], v[178:179]
	v_pk_fma_f32 v[178:179], v[52:53], v[120:121], v[178:179]
	v_pk_fma_f32 v[194:195], v[54:55], v[118:119], v[194:195]
	v_pk_fma_f32 v[194:195], v[56:57], v[120:121], v[194:195]
	ds_read_b128 v[118:121], v131 offset:5152
	s_waitcnt vmcnt(16)
	s_waitcnt lgkmcnt(7)
	v_pk_fma_f32 v[132:133], v[58:59], v[90:91], v[132:133]
	v_pk_fma_f32 v[132:133], v[60:61], v[92:93], v[132:133]
	v_pk_fma_f32 v[148:149], v[62:63], v[90:91], v[148:149]
	v_pk_fma_f32 v[148:149], v[64:65], v[92:93], v[148:149]
	v_pk_fma_f32 v[164:165], v[66:67], v[90:91], v[164:165]
	v_pk_fma_f32 v[164:165], v[68:69], v[92:93], v[164:165]
	v_pk_fma_f32 v[180:181], v[70:71], v[90:91], v[180:181]
	v_pk_fma_f32 v[180:181], v[72:73], v[92:93], v[180:181]
	ds_read_b128 v[90:93], v131 offset:3376
	s_waitcnt lgkmcnt(7)
	v_pk_fma_f32 v[134:135], v[58:59], v[94:95], v[134:135]
	v_pk_fma_f32 v[134:135], v[60:61], v[96:97], v[134:135]
	v_pk_fma_f32 v[150:151], v[62:63], v[94:95], v[150:151]
	v_pk_fma_f32 v[150:151], v[64:65], v[96:97], v[150:151]
	v_pk_fma_f32 v[166:167], v[66:67], v[94:95], v[166:167]
	v_pk_fma_f32 v[166:167], v[68:69], v[96:97], v[166:167]
	v_pk_fma_f32 v[182:183], v[70:71], v[94:95], v[182:183]
	v_pk_fma_f32 v[182:183], v[72:73], v[96:97], v[182:183]
	ds_read_b128 v[94:97], v131 offset:3632
	s_waitcnt lgkmcnt(7)
	v_pk_fma_f32 v[136:137], v[58:59], v[98:99], v[136:137]
	v_pk_fma_f32 v[136:137], v[60:61], v[100:101], v[136:137]
	v_pk_fma_f32 v[152:153], v[62:63], v[98:99], v[152:153]
	v_pk_fma_f32 v[152:153], v[64:65], v[100:101], v[152:153]
	v_pk_fma_f32 v[168:169], v[66:67], v[98:99], v[168:169]
	v_pk_fma_f32 v[168:169], v[68:69], v[100:101], v[168:169]
	v_pk_fma_f32 v[184:185], v[70:71], v[98:99], v[184:185]
	v_pk_fma_f32 v[184:185], v[72:73], v[100:101], v[184:185]
	ds_read_b128 v[98:101], v131 offset:3888
	s_waitcnt lgkmcnt(7)
	v_pk_fma_f32 v[138:139], v[58:59], v[102:103], v[138:139]
	v_pk_fma_f32 v[138:139], v[60:61], v[104:105], v[138:139]
	v_pk_fma_f32 v[154:155], v[62:63], v[102:103], v[154:155]
	v_pk_fma_f32 v[154:155], v[64:65], v[104:105], v[154:155]
	v_pk_fma_f32 v[170:171], v[66:67], v[102:103], v[170:171]
	v_pk_fma_f32 v[170:171], v[68:69], v[104:105], v[170:171]
	v_pk_fma_f32 v[186:187], v[70:71], v[102:103], v[186:187]
	v_pk_fma_f32 v[186:187], v[72:73], v[104:105], v[186:187]
	ds_read_b128 v[102:105], v131 offset:4144
	s_waitcnt lgkmcnt(7)
	v_pk_fma_f32 v[140:141], v[58:59], v[106:107], v[140:141]
	v_pk_fma_f32 v[140:141], v[60:61], v[108:109], v[140:141]
	v_pk_fma_f32 v[156:157], v[62:63], v[106:107], v[156:157]
	v_pk_fma_f32 v[156:157], v[64:65], v[108:109], v[156:157]
	v_pk_fma_f32 v[172:173], v[66:67], v[106:107], v[172:173]
	v_pk_fma_f32 v[172:173], v[68:69], v[108:109], v[172:173]
	v_pk_fma_f32 v[188:189], v[70:71], v[106:107], v[188:189]
	v_pk_fma_f32 v[188:189], v[72:73], v[108:109], v[188:189]
	ds_read_b128 v[106:109], v131 offset:4400
	s_waitcnt lgkmcnt(7)
	v_pk_fma_f32 v[142:143], v[58:59], v[110:111], v[142:143]
	v_pk_fma_f32 v[142:143], v[60:61], v[112:113], v[142:143]
	v_pk_fma_f32 v[158:159], v[62:63], v[110:111], v[158:159]
	v_pk_fma_f32 v[158:159], v[64:65], v[112:113], v[158:159]
	v_pk_fma_f32 v[174:175], v[66:67], v[110:111], v[174:175]
	v_pk_fma_f32 v[174:175], v[68:69], v[112:113], v[174:175]
	v_pk_fma_f32 v[190:191], v[70:71], v[110:111], v[190:191]
	v_pk_fma_f32 v[190:191], v[72:73], v[112:113], v[190:191]
	ds_read_b128 v[110:113], v131 offset:4656
	s_waitcnt lgkmcnt(7)
	v_pk_fma_f32 v[144:145], v[58:59], v[114:115], v[144:145]
	v_pk_fma_f32 v[144:145], v[60:61], v[116:117], v[144:145]
	v_pk_fma_f32 v[160:161], v[62:63], v[114:115], v[160:161]
	v_pk_fma_f32 v[160:161], v[64:65], v[116:117], v[160:161]
	v_pk_fma_f32 v[176:177], v[66:67], v[114:115], v[176:177]
	v_pk_fma_f32 v[176:177], v[68:69], v[116:117], v[176:177]
	v_pk_fma_f32 v[192:193], v[70:71], v[114:115], v[192:193]
	v_pk_fma_f32 v[192:193], v[72:73], v[116:117], v[192:193]
	ds_read_b128 v[114:117], v131 offset:4912
	s_waitcnt lgkmcnt(7)
	v_pk_fma_f32 v[146:147], v[58:59], v[118:119], v[146:147]
	v_pk_fma_f32 v[146:147], v[60:61], v[120:121], v[146:147]
	v_pk_fma_f32 v[162:163], v[62:63], v[118:119], v[162:163]
	v_pk_fma_f32 v[162:163], v[64:65], v[120:121], v[162:163]
	v_pk_fma_f32 v[178:179], v[66:67], v[118:119], v[178:179]
	v_pk_fma_f32 v[178:179], v[68:69], v[120:121], v[178:179]
	v_pk_fma_f32 v[194:195], v[70:71], v[118:119], v[194:195]
	v_pk_fma_f32 v[194:195], v[72:73], v[120:121], v[194:195]
	ds_read_b128 v[118:121], v131 offset:5168
	s_waitcnt vmcnt(0)
	s_waitcnt lgkmcnt(7)
	v_pk_fma_f32 v[132:133], v[74:75], v[90:91], v[132:133]
	v_pk_fma_f32 v[132:133], v[76:77], v[92:93], v[132:133]
	v_pk_fma_f32 v[148:149], v[78:79], v[90:91], v[148:149]
	v_pk_fma_f32 v[148:149], v[80:81], v[92:93], v[148:149]
	v_pk_fma_f32 v[164:165], v[82:83], v[90:91], v[164:165]
	v_pk_fma_f32 v[164:165], v[84:85], v[92:93], v[164:165]
	v_pk_fma_f32 v[180:181], v[86:87], v[90:91], v[180:181]
	v_pk_fma_f32 v[180:181], v[88:89], v[92:93], v[180:181]
	s_waitcnt lgkmcnt(6)
	v_pk_fma_f32 v[134:135], v[74:75], v[94:95], v[134:135]
	v_pk_fma_f32 v[134:135], v[76:77], v[96:97], v[134:135]
	v_pk_fma_f32 v[150:151], v[78:79], v[94:95], v[150:151]
	v_pk_fma_f32 v[150:151], v[80:81], v[96:97], v[150:151]
	v_pk_fma_f32 v[166:167], v[82:83], v[94:95], v[166:167]
	v_pk_fma_f32 v[166:167], v[84:85], v[96:97], v[166:167]
	v_pk_fma_f32 v[182:183], v[86:87], v[94:95], v[182:183]
	v_pk_fma_f32 v[182:183], v[88:89], v[96:97], v[182:183]
	s_waitcnt lgkmcnt(5)
	v_pk_fma_f32 v[136:137], v[74:75], v[98:99], v[136:137]
	v_pk_fma_f32 v[136:137], v[76:77], v[100:101], v[136:137]
	v_pk_fma_f32 v[152:153], v[78:79], v[98:99], v[152:153]
	v_pk_fma_f32 v[152:153], v[80:81], v[100:101], v[152:153]
	v_pk_fma_f32 v[168:169], v[82:83], v[98:99], v[168:169]
	v_pk_fma_f32 v[168:169], v[84:85], v[100:101], v[168:169]
	v_pk_fma_f32 v[184:185], v[86:87], v[98:99], v[184:185]
	v_pk_fma_f32 v[184:185], v[88:89], v[100:101], v[184:185]
	s_waitcnt lgkmcnt(4)
	v_pk_fma_f32 v[138:139], v[74:75], v[102:103], v[138:139]
	v_pk_fma_f32 v[138:139], v[76:77], v[104:105], v[138:139]
	v_pk_fma_f32 v[154:155], v[78:79], v[102:103], v[154:155]
	v_pk_fma_f32 v[154:155], v[80:81], v[104:105], v[154:155]
	v_pk_fma_f32 v[170:171], v[82:83], v[102:103], v[170:171]
	v_pk_fma_f32 v[170:171], v[84:85], v[104:105], v[170:171]
	v_pk_fma_f32 v[186:187], v[86:87], v[102:103], v[186:187]
	v_pk_fma_f32 v[186:187], v[88:89], v[104:105], v[186:187]
	s_waitcnt lgkmcnt(3)
	v_pk_fma_f32 v[140:141], v[74:75], v[106:107], v[140:141]
	v_pk_fma_f32 v[140:141], v[76:77], v[108:109], v[140:141]
	v_pk_fma_f32 v[156:157], v[78:79], v[106:107], v[156:157]
	v_pk_fma_f32 v[156:157], v[80:81], v[108:109], v[156:157]
	v_pk_fma_f32 v[172:173], v[82:83], v[106:107], v[172:173]
	v_pk_fma_f32 v[172:173], v[84:85], v[108:109], v[172:173]
	v_pk_fma_f32 v[188:189], v[86:87], v[106:107], v[188:189]
	v_pk_fma_f32 v[188:189], v[88:89], v[108:109], v[188:189]
	s_waitcnt lgkmcnt(2)
	v_pk_fma_f32 v[142:143], v[74:75], v[110:111], v[142:143]
	v_pk_fma_f32 v[142:143], v[76:77], v[112:113], v[142:143]
	v_pk_fma_f32 v[158:159], v[78:79], v[110:111], v[158:159]
	v_pk_fma_f32 v[158:159], v[80:81], v[112:113], v[158:159]
	v_pk_fma_f32 v[174:175], v[82:83], v[110:111], v[174:175]
	v_pk_fma_f32 v[174:175], v[84:85], v[112:113], v[174:175]
	v_pk_fma_f32 v[190:191], v[86:87], v[110:111], v[190:191]
	v_pk_fma_f32 v[190:191], v[88:89], v[112:113], v[190:191]
	s_waitcnt lgkmcnt(1)
	v_pk_fma_f32 v[144:145], v[74:75], v[114:115], v[144:145]
	v_pk_fma_f32 v[144:145], v[76:77], v[116:117], v[144:145]
	v_pk_fma_f32 v[160:161], v[78:79], v[114:115], v[160:161]
	v_pk_fma_f32 v[160:161], v[80:81], v[116:117], v[160:161]
	v_pk_fma_f32 v[176:177], v[82:83], v[114:115], v[176:177]
	v_pk_fma_f32 v[176:177], v[84:85], v[116:117], v[176:177]
	v_pk_fma_f32 v[192:193], v[86:87], v[114:115], v[192:193]
	v_pk_fma_f32 v[192:193], v[88:89], v[116:117], v[192:193]
	s_waitcnt lgkmcnt(0)
	v_pk_fma_f32 v[146:147], v[74:75], v[118:119], v[146:147]
	v_pk_fma_f32 v[146:147], v[76:77], v[120:121], v[146:147]
	v_pk_fma_f32 v[162:163], v[78:79], v[118:119], v[162:163]
	v_pk_fma_f32 v[162:163], v[80:81], v[120:121], v[162:163]
	v_pk_fma_f32 v[178:179], v[82:83], v[118:119], v[178:179]
	v_pk_fma_f32 v[178:179], v[84:85], v[120:121], v[178:179]
	v_pk_fma_f32 v[194:195], v[86:87], v[118:119], v[194:195]
	v_pk_fma_f32 v[194:195], v[88:89], v[120:121], v[194:195]
	v_add_f32_e32 v132, v132, v133
	v_add_f32_e32 v134, v134, v135
	v_add_f32_e32 v136, v136, v137
	v_add_f32_e32 v138, v138, v139
	v_add_f32_e32 v140, v140, v141
	v_add_f32_e32 v142, v142, v143
	v_add_f32_e32 v144, v144, v145
	v_add_f32_e32 v146, v146, v147
	v_add_f32_e32 v148, v148, v149
	v_add_f32_e32 v150, v150, v151
	v_add_f32_e32 v152, v152, v153
	v_add_f32_e32 v154, v154, v155
	v_add_f32_e32 v156, v156, v157
	v_add_f32_e32 v158, v158, v159
	v_add_f32_e32 v160, v160, v161
	v_add_f32_e32 v162, v162, v163
	v_add_f32_e32 v164, v164, v165
	v_add_f32_e32 v166, v166, v167
	v_add_f32_e32 v168, v168, v169
	v_add_f32_e32 v170, v170, v171
	v_add_f32_e32 v172, v172, v173
	v_add_f32_e32 v174, v174, v175
	v_add_f32_e32 v176, v176, v177
	v_add_f32_e32 v178, v178, v179
	v_add_f32_e32 v180, v180, v181
	v_add_f32_e32 v182, v182, v183
	v_add_f32_e32 v184, v184, v185
	v_add_f32_e32 v186, v186, v187
	v_add_f32_e32 v188, v188, v189
	v_add_f32_e32 v190, v190, v191
	v_add_f32_e32 v192, v192, v193
	v_add_f32_e32 v194, v194, v195
	s_branch .LBB0_481

.LBB0_481:
	s_cmp_eq_u32 s52, 0
	s_cbranch_scc1 .Lf3_q0
	s_cmp_eq_u32 s52, 1
	s_cbranch_scc1 .Lf3_q1
	s_cmp_eq_u32 s52, 2
	s_cbranch_scc1 .Lf3_q2
	v_mov_b32_e32 v10, v180
	v_mov_b32_e32 v11, v182
	v_mov_b32_e32 v8, v184
	v_mov_b32_e32 v9, v186
	v_mov_b32_e32 v6, v188
	v_mov_b32_e32 v7, v190
	v_mov_b32_e32 v4, v192
	v_mov_b32_e32 v5, v194
	s_branch .Lf3_epi
.Lf3_q0:
	v_mov_b32_e32 v10, v132
	v_mov_b32_e32 v11, v134
	v_mov_b32_e32 v8, v136
	v_mov_b32_e32 v9, v138
	v_mov_b32_e32 v6, v140
	v_mov_b32_e32 v7, v142
	v_mov_b32_e32 v4, v144
	v_mov_b32_e32 v5, v146
	s_branch .Lf3_epi
.Lf3_q1:
	v_mov_b32_e32 v10, v148
	v_mov_b32_e32 v11, v150
	v_mov_b32_e32 v8, v152
	v_mov_b32_e32 v9, v154
	v_mov_b32_e32 v6, v156
	v_mov_b32_e32 v7, v158
	v_mov_b32_e32 v4, v160
	v_mov_b32_e32 v5, v162
	s_branch .Lf3_epi
.Lf3_q2:
	v_mov_b32_e32 v10, v164
	v_mov_b32_e32 v11, v166
	v_mov_b32_e32 v8, v168
	v_mov_b32_e32 v9, v170
	v_mov_b32_e32 v6, v172
	v_mov_b32_e32 v7, v174
	v_mov_b32_e32 v4, v176
	v_mov_b32_e32 v5, v178
.Lf3_epi:
	s_and_b64 vcc, exec, s[28:29]
	s_cbranch_vccnz .Lf3_slow
	v_lshl_add_u32 v12, s52, 8, v0
	v_and_b32_e32 v12, 0x1ff, v12
	v_cvt_f32_u32_e32 v13, v12
	s_nop 0
	v_fmamk_f32 v26, v13, 0x3cc4df2d, v250
	v_mul_f32_e32 v32, v18, v26
	v_mul_f32_e32 v33, v19, v26
	v_mul_f32_e32 v34, v20, v26
	v_mul_f32_e32 v35, v21, v26
	v_mul_f32_e32 v36, v22, v26
	v_mul_f32_e32 v37, v23, v26
	v_mul_f32_e32 v38, v24, v26
	v_mul_f32_e32 v39, v25, v26
	v_mul_f32_e32 v32, 0x3fb8aa3b, v32
	v_mul_f32_e32 v33, 0x3fb8aa3b, v33
	v_mul_f32_e32 v34, 0x3fb8aa3b, v34
	v_mul_f32_e32 v35, 0x3fb8aa3b, v35
	v_mul_f32_e32 v36, 0x3fb8aa3b, v36
	v_mul_f32_e32 v37, 0x3fb8aa3b, v37
	v_mul_f32_e32 v38, 0x3fb8aa3b, v38
	v_mul_f32_e32 v39, 0x3fb8aa3b, v39
	v_exp_f32_e32 v32, v32
	v_exp_f32_e32 v33, v33
	v_exp_f32_e32 v34, v34
	v_exp_f32_e32 v35, v35
	v_exp_f32_e32 v36, v36
	v_exp_f32_e32 v37, v37
	v_exp_f32_e32 v38, v38
	v_exp_f32_e32 v39, v39
	v_mul_u32_u24_e32 v12, s54, v12
	v_lshlrev_b32_e32 v130, 1, v12
	v_mul_f32_e32 v10, v32, v10
	v_mul_f32_e32 v11, v33, v11
	v_mul_f32_e32 v8, v34, v8
	v_mul_f32_e32 v9, v35, v9
	v_mul_f32_e32 v6, v36, v6
	v_mul_f32_e32 v7, v37, v7
	v_mul_f32_e32 v4, v38, v4
	v_mul_f32_e32 v5, v39, v5
	v_bfe_u32 v32, v10, 16, 1
	v_bfe_u32 v33, v11, 16, 1
	v_bfe_u32 v34, v8, 16, 1
	v_bfe_u32 v35, v9, 16, 1
	v_bfe_u32 v36, v6, 16, 1
	v_bfe_u32 v37, v7, 16, 1
	v_bfe_u32 v38, v4, 16, 1
	v_bfe_u32 v39, v5, 16, 1
	v_add3_u32 v10, v10, v32, s91
	v_add3_u32 v11, v11, v33, s91
	v_add3_u32 v8, v8, v34, s91
	v_add3_u32 v9, v9, v35, s91
	v_add3_u32 v6, v6, v36, s91
	v_add3_u32 v7, v7, v37, s91
	v_add3_u32 v4, v4, v38, s91
	v_add3_u32 v5, v5, v39, s91
	v_lshl_add_u64 v[14:15], s[0:1], 0, v[130:131]
	s_mov_b32 s37, 0x7060302
	s_lshl_b32 s92, s53, 1
	s_cmp_lt_u32 s52, 2
	s_cbranch_scc0 .Lf3_caseB
	s_lshl_b32 s46, s50, 1
	v_perm_b32 v28, v4, v5, s37
	v_perm_b32 v29, v6, v7, s37
	v_perm_b32 v30, v8, v9, s37
	v_perm_b32 v31, v10, v11, s37
	s_branch .Lf3_st
